# attn loops hand-scheduled (2 q-blocks interleaved, permlane32 swap, saddr DMA), bias table prefetched in P0, no store drain at unit start
# speedup vs baseline: 1.0083x; 1.0083x over previous
; #define KP() ({ KArgs _p = kp; asm volatile("" : "+s"(_p)); _p; })
; DI void prologue(KArgs ap, int gw, int NGW, int lane) {
;     unsigned char* ws = ap->ws;
;     const float *xp = ap->in[0], *xs = ap->in[1], *g_attn = ap->in[7], *w_in = ap->in[8];
;     { unsigned* z = (unsigned*)(ws + WS_X1B); for (int i = gw * 64 + lane; i < 2 * DM / 2; i += NGW * 64) z[i] = 0u;
;       if (gw == 1) { float* gd = (float*)(ws + WS_GAINS); gd[lane] = ap->in[9][lane]; gd[64 + lane] = ap->in[10][lane]; gd[128 + lane] = ap->in[12][lane]; gd[192 + lane] = ap->in[13][lane]; } }
; __global__ void __launch_bounds__(512, 2) fwd_kernel(Args a_byval) {
;     ...
;         { const float* tab = KP()->in[11]; for (int i = tid; i < 8 * 256; i += 512) { const int h = i >> 8, uu = i & 255; int d = 191 - uu; d = d > 128 ? 128 : d; biasL[i] = tab[h * 257 + d + 128] * LOG2E; } }
.LBB0_19:
	s_lshr_b32 s60, s19, 6
	s_cmp_lt_i32 s38, 1
	s_cselect_b64 s[0:1], -1, 0
	s_cmp_gt_i32 s39, 0
	s_cselect_b64 s[4:5], -1, 0
	s_and_b64 s[0:1], s[0:1], s[4:5]
	s_andn2_b64 vcc, exec, s[0:1]
	v_and_b32_e32 v190, 63, v226
	s_cbranch_vccnz .LBB0_41
	v_readlane_b32 s98, v253, 1
	v_readlane_b32 s99, v253, 2
	s_movk_i32 s32, 0xbf
	s_load_dwordx2 s[98:99], s[98:99], 0x58
	v_sub_u32_sdwa v240, s32, v226 dst_sel:DWORD dst_unused:UNUSED_PAD src0_sel:DWORD src1_sel:BYTE_0
	v_lshrrev_b32_e32 v241, 8, v226
	s_movk_i32 s32, 0x101
	v_min_i32_e32 v240, 0x80, v240
	v_mad_u32_u24 v240, v241, s32, v240
	v_add_u32_e32 v240, 0x80, v240
	v_lshlrev_b32_e32 v240, 2, v240
	v_add_u32_e32 v241, 0x808, v240
	v_add_u32_e32 v242, 0x1010, v240
	v_add_u32_e32 v243, 0x1818, v240
	s_waitcnt lgkmcnt(0)
	global_load_dword v240, v240, s[98:99]
	global_load_dword v241, v241, s[98:99]
	global_load_dword v242, v242, s[98:99]
	global_load_dword v243, v243, s[98:99]
	v_readlane_b32 s20, v253, 1
	v_readlane_b32 s21, v253, 2
	s_load_dwordx2 s[16:17], s[20:21], 0xb0
	s_load_dwordx4 s[8:11], s[20:21], 0x0
	s_load_dwordx4 s[12:15], s[20:21], 0x38
	s_lshl_b32 s4, s2, 3
	s_add_i32 s6, s60, s4
	v_lshl_or_b32 v0, s6, 6, v190
	s_movk_i32 s4, 0x400
	v_readlane_b32 s5, v253, 0
	v_cmp_gt_i32_e32 vcc, s4, v0
	s_lshl_b32 s18, s5, 9
	s_and_saveexec_b64 s[22:23], vcc
	s_cbranch_execz .LBB0_28
	v_cvt_f32_u32_e32 v1, s18
	v_readlane_b32 s5, v253, 0
	s_add_i32 s5, s2, s5
	s_andn2_b32 s19, s19, 63
	v_rcp_iflag_f32_e32 v1, v1
	s_lshl_b32 s5, s5, 9
	s_add_i32 s5, s5, s19
	v_or_b32_e32 v2, s5, v190
	v_mul_f32_e32 v1, 0x4f7ffffe, v1
	v_cvt_u32_f32_e32 v1, v1
	v_cmp_gt_i32_e32 vcc, s4, v2
	v_max_i32_e32 v3, 0x400, v2
	s_mov_b64 s[24:25], -1
	v_addc_co_u32_e64 v2, s[4:5], 0, v2, vcc
	s_sub_i32 s4, 0, s18
	v_sub_u32_e32 v2, v3, v2
	v_mul_lo_u32 v3, s4, v1
	v_mul_hi_u32 v3, v1, v3
	v_add_u32_e32 v1, v1, v3
	v_mul_hi_u32 v1, v2, v1
	v_mul_lo_u32 v3, v1, s18
	v_sub_u32_e32 v2, v2, v3
	v_add_u32_e32 v3, 1, v1
	v_cmp_le_u32_e64 s[4:5], s18, v2
	s_nop 1
	v_cndmask_b32_e64 v1, v1, v3, s[4:5]
	v_subrev_u32_e32 v3, s18, v2
	v_cndmask_b32_e64 v2, v2, v3, s[4:5]
	v_add_u32_e32 v3, 1, v1
	v_cmp_le_u32_e64 s[4:5], s18, v2
	v_mov_b32_e32 v2, v0
	s_nop 0
	v_cndmask_b32_e64 v1, v1, v3, s[4:5]
	v_addc_co_u32_e32 v4, vcc, 1, v1, vcc
	v_cmp_lt_u32_e32 vcc, 1, v4
	s_and_saveexec_b64 s[4:5], vcc
	s_cbranch_execz .LBB0_25
	s_waitcnt lgkmcnt(0)
	s_add_u32 s24, s16, 0x1900000
	v_readlane_b32 s7, v253, 0
	s_addc_u32 s25, s17, 0
	v_and_b32_e32 v5, -2, v4
	v_add_u32_e32 v1, s18, v0
	s_lshl_b32 s7, s7, 10
	s_mov_b32 s19, s7
	s_mov_b64 s[26:27], 0
	v_mov_b32_e32 v6, 0
	v_mov_b32_e32 v7, v5
	v_mov_b64_e32 v[2:3], v[0:1]

; #define KP() ({ KArgs _p = kp; asm volatile("" : "+s"(_p)); _p; })
; DI void prologue(KArgs ap, int gw, int NGW, int lane) {
;     ...
;         for (int m = gw; m < MTOK; m += NGW) {
;             const f32x4* xr = (const f32x4*)(m < SEQ ? xp + (size_t)m * DM : xs + (size_t)(m - SEQ) * DM) + lane;
; __global__ void __launch_bounds__(512, 2) fwd_kernel(Args a_byval) {
;     ...
;         { const float* tab = KP()->in[11]; for (int i = tid; i < 8 * 256; i += 512) { const int h = i >> 8, uu = i & 255; int d = 191 - uu; d = d > 128 ? 128 : d; biasL[i] = tab[h * 257 + d + 128] * LOG2E; } }
.LBB0_39:
	s_cmpk_lt_i32 s6, 0x4000
	s_mov_b64 s[16:17], s[6:7]
	s_mov_b64 s[18:19], s[8:9]
	s_cbranch_scc1 .LBB0_38
	s_add_i32 s12, s6, 0xffffc000
	s_lshl_b64 s[16:17], s[12:13], 12
	s_add_u32 s18, s10, s16
	s_mov_b32 s12, s6
	s_addc_u32 s19, s11, s17
	s_mov_b64 s[16:17], s[12:13]
	s_branch .LBB0_38
	s_branch .Lbt_fill
.Lbt_fill:
	s_waitcnt vmcnt(0)
	v_lshlrev_b32_e32 v244, 2, v226
	v_mul_f32_e32 v240, 0x3fb8aa3b, v240
	v_mul_f32_e32 v241, 0x3fb8aa3b, v241
	v_add_u32_e32 v244, 0x22100, v244
	v_mul_f32_e32 v242, 0x3fb8aa3b, v242
	v_mul_f32_e32 v243, 0x3fb8aa3b, v243
	ds_write_b32 v244, v240
	ds_write_b32 v244, v241 offset:2048
	ds_write_b32 v244, v242 offset:4096
	ds_write_b32 v244, v243 offset:6144

; #define LAS __attribute__((address_space(3)))
; #define KP() ({ KArgs _p = kp; asm volatile("" : "+s"(_p)); _p; })
; __global__ void __launch_bounds__(512, 2) fwd_kernel(Args a_byval) {
;     ...
;     if (IN(2)) {
;         LAS float* biasL = (LAS float*)(lds + RING_BYTES + 8448);
;         { const float* tab = KP()->in[11]; for (int i = tid; i < 8 * 256; i += 512) { const int h = i >> 8, uu = i & 255; int d = 191 - uu; d = d > 128 ? 128 : d; biasL[i] = tab[h * 257 + d + 128] * LOG2E; } }
.LBB0_597:
	s_cmp_lt_i32 s38, 3
	s_cselect_b64 s[4:5], -1, 0
	s_and_b64 s[10:11], s[4:5], s[0:1]
	s_andn2_b64 vcc, exec, s[10:11]
	s_cbranch_vccnz .LBB0_712
	s_cmp_lt_i32 s38, 1
	s_cbranch_scc1 .Lbt_skip
	v_readlane_b32 s0, v253, 1
	v_readlane_b32 s1, v253, 2
	s_load_dwordx2 s[0:1], s[0:1], 0x58
	s_movk_i32 s4, 0xbf
	v_sub_u32_sdwa v0, s4, v226 dst_sel:DWORD dst_unused:UNUSED_PAD src0_sel:DWORD src1_sel:BYTE_0
	v_lshl_add_u32 v3, v226, 2, 0
	v_min_i32_e32 v0, 0x80, v0
	v_add_u32_e32 v1, 0xfffffe00, v226
	v_lshrrev_b32_e32 v2, 8, v226
	v_add_u32_e32 v3, 0x22100, v3
	s_mov_b64 s[4:5], 0
	s_movk_i32 s6, 0x101
	s_movk_i32 s7, 0x5ff

; #define LAS __attribute__((address_space(3)))
; #define KP() ({ KArgs _p = kp; asm volatile("" : "+s"(_p)); _p; })
; template <bool ISB>
; DI void attn_unit(int u, int hq, int qoff, int nq, const bf16_t* Qb, const bf16_t* Kb, const bf16_t* Vtb, bf16_t* O, const float* sinks, const LAS float* biasL, LAS unsigned char* ring, int lane) {
;     ...
;     const int r = lane & 31, hh = lane >> 5;
;     const int hk = ISB ? (hq >> 2) : hq;
;     int kbase, j0;
;     if (u < 256) { kbase = 64 * (u - (NCH - 1)); j0 = (NCH - 1) - u; if (j0 < 0) j0 = 0; } else { kbase = SEQ + (u - 256) * (64 * NCH); j0 = 0; }
;     const bf16_t* Qp = Qb + ((size_t)hq * MTOK + 64 * u + qoff) * 64;
;     const bf16_t* Kp = Kb + (size_t)hk * KROWS * 64 + 8 * lane;
;     const bf16_t* Vp = Vtb + (size_t)hk * KROWS * 64 + 8 * lane;
; __global__ void __launch_bounds__(512, 2) fwd_kernel(Args a_byval) {
;     ...
;         const float* sinks = KP()->in[14];
;         __syncthreads();
;         volatile LAS unsigned* wctr = (volatile LAS unsigned*)(lds + RING_BYTES + 8192 + 64);
;         if (tid == 0) *wctr = 0u;
;         __syncthreads();
.Lbt_skip:
	v_readlane_b32 s0, v253, 1
	v_readlane_b32 s1, v253, 2
	s_load_dwordx2 s[0:1], s[0:1], 0x70
	s_mov_b32 s13, 0
	v_cmp_eq_u32_e32 vcc, 0, v226
	s_waitcnt lgkmcnt(0)
	s_barrier
	s_and_saveexec_b64 s[4:5], vcc
	s_add_i32 s6, 0, 0x22040
	v_mov_b32_e32 v0, 0
	v_mov_b32_e32 v1, s6
	ds_write_b32 v1, v0
	s_or_b64 exec, exec, s[4:5]
	s_lshl_b32 s4, s60, 14
	s_add_i32 s31, s4, 0
	s_bfe_u32 s4, s2, 0x10002
	s_add_i32 s30, s2, 0xfffff600
	s_and_b32 s6, s2, 7
	s_mul_i32 s4, s4, 0x2c0000
	v_mov_b32_e32 v161, 0
	s_add_u32 s4, s36, s4
	v_lshrrev_b32_e32 v8, 5, v190
	v_lshlrev_b32_e32 v158, 4, v190
	v_mov_b32_e32 v159, v161
	s_addc_u32 s5, s37, 0
	v_and_b32_e32 v182, 31, v226
	v_lshl_add_u64 v[0:1], s[4:5], 0, v[158:159]
	s_mov_b64 s[4:5], 0x8400000
	v_lshlrev_b32_e32 v2, 4, v8
	v_mov_b32_e32 v3, v161
	v_lshl_add_u64 v[162:163], v[0:1], 0, s[4:5]
	s_mov_b64 s[4:5], 0x8a00000
	v_lshlrev_b32_e32 v4, 7, v182
	v_mov_b32_e32 v5, v161
	v_lshl_add_u64 v[6:7], s[36:37], 0, v[2:3]
	v_lshl_add_u64 v[164:165], v[0:1], 0, s[4:5]
	v_lshl_add_u64 v[4:5], v[6:7], 0, v[4:5]
	s_mov_b64 s[4:5], 0xc600000
	v_lshl_add_u64 v[166:167], v[4:5], 0, s[4:5]
	s_lshl_b32 s4, s6, 2
	s_add_u32 s14, s0, s4
	s_addc_u32 s15, s1, 0
	s_mul_i32 s0, s6, 0x440000
	s_add_u32 s0, s36, s0
	s_addc_u32 s1, s37, 0
	v_lshl_add_u64 v[4:5], s[0:1], 0, v[158:159]
	s_mov_b64 s[0:1], 0xd800000
	v_lshl_add_u64 v[168:169], v[4:5], 0, s[0:1]
	s_mov_b64 s[0:1], 0x6200000
	v_lshl_add_u64 v[170:171], v[4:5], 0, s[0:1]
	s_mov_b64 s[0:1], 0xb400000
	v_lshl_add_u64 v[172:173], v[6:7], 0, s[0:1]
	s_lshl_b32 s0, s6, 10
	s_add_i32 s4, s0, 0
	s_add_i32 s34, s4, 0x22100
	s_lshl_b32 s0, s6, 7
	s_add_u32 s0, s36, s0
	v_lshlrev_b32_e32 v160, 3, v8
	v_mov_b32_e32 v1, 0xfffffe00
	s_addc_u32 s1, s37, 0
	v_lshlrev_b32_e32 v0, 6, v182
	v_cmp_gt_u32_e32 vcc, 32, v190
	v_lshl_or_b32 v159, v8, 2, v1
	v_lshl_add_u64 v[4:5], s[0:1], 0, v[160:161]
	s_mov_b64 s[0:1], 0x3e00000
	v_add_u32_e32 v1, s4, v2
	v_mbcnt_lo_u32_b32 v185, -1, 0
	v_cmp_eq_u32_e64 s[8:9], 0, v190
	s_mul_i32 s33, s6, 0x4800
	v_cndmask_b32_e64 v183, 0, 1.0, vcc
	s_add_i32 s35, s2, 0xffffed00
	v_lshl_add_u64 v[174:175], v[4:5], 0, s[0:1]
	v_add_u32_e32 v184, 0x21c7c, v1
	s_add_i32 s42, 0, 0x22040
	s_mov_b64 s[16:17], 0x400
	s_add_i32 s43, s31, 0x400
	s_mov_b64 s[18:19], 0x800
	s_add_i32 s44, s31, 0x800
	s_mov_b64 s[20:21], 0xc00
	s_add_i32 s45, s31, 0xc00
	s_add_i32 s46, s31, 0x1000
	s_add_i32 s47, s31, 0x1400
	s_add_i32 s48, s31, 0x1800
	s_add_i32 s49, s31, 0x1c00
	s_add_i32 s50, s31, 0x2000
	s_add_i32 s51, s31, 0x2400
	s_add_i32 s52, s31, 0x2800
	s_add_i32 s53, s31, 0x2c00
	s_add_i32 s54, s31, 0x3000
	s_add_i32 s55, s31, 0x3400
	s_add_i32 s56, s31, 0x3800
	s_add_i32 s57, s31, 0x3c00
	s_mov_b32 s58, 0x3fb8aa3b
	v_mov_b32_e32 v177, 0x41000000
	v_lshlrev_b32_e32 v160, 1, v0
	s_mov_b32 s59, 0x10000
	s_mov_b32 s60, 0x1b000
	s_mov_b32 s61, 0x26000
	s_mov_b32 s62, 0x31000
	s_mov_b32 s63, 0x3c000
	s_mov_b32 s64, 0x47000
	s_mov_b32 s65, 0x52000
	s_mov_b32 s66, 0x5d000
	s_mov_b32 s67, 0x68000
	s_mov_b32 s68, 0x73000
	s_mov_b32 s69, 0x7e000
	s_mov_b32 s70, 0x89000
	s_mov_b32 s71, 0x94000
	s_mov_b32 s72, 0x9f000
	s_mov_b32 s73, 0xaa000
	s_mov_b32 s74, 0xb5000
	s_mov_b32 s75, 0xc0000
	s_mov_b32 s76, 0xcb000
	s_mov_b32 s77, 0xd6000
	s_mov_b32 s78, 0xe1000
	s_mov_b32 s79, 0xec000
	s_mov_b32 s80, 0xf7000
	s_mov_b32 s81, 0x102000
	s_mov_b32 s82, 0x10d000
	s_mov_b32 s83, 0x118000
	s_mov_b32 s84, 0x123000
	s_mov_b32 s85, 0x12e000
	s_mov_b32 s86, 0x139000
	s_mov_b32 s87, 0x144000
	s_mov_b32 s88, 0x14f000
	s_mov_b32 s89, 0x15a000
	s_mov_b64 s[22:23], 0x800000
	s_mov_b64 s[24:25], 0x600000
	s_mov_b32 s90, 0x600000
	v_mbcnt_hi_u32_b32 v186, -1, v185
	v_mov_b32_e32 v187, 0xf149f2ca
	s_waitcnt lgkmcnt(0)
	s_barrier
	s_branch .LBB0_605

; #define LAS __attribute__((address_space(3)))
; template <bool ISB>
; DI void attn_unit(int u, int hq, int qoff, int nq, const bf16_t* Qb, const bf16_t* Kb, const bf16_t* Vtb, bf16_t* O, const float* sinks, const LAS float* biasL, LAS unsigned char* ring, int lane) {
;     ...
;     if (u < 256) { kbase = 64 * (u - (NCH - 1)); j0 = (NCH - 1) - u; if (j0 < 0) j0 = 0; } else { kbase = SEQ + (u - 256) * (64 * NCH); j0 = 0; }
;     const bf16_t* Qp = Qb + ((size_t)hq * MTOK + 64 * u + qoff) * 64;
;     const bf16_t* Kp = Kb + (size_t)hk * KROWS * 64 + 8 * lane;
;     const bf16_t* Vp = Vtb + (size_t)hk * KROWS * 64 + 8 * lane;
;     const int kb0 = 2 * j0, kbN = 2 * NCH, blk0 = (kbase >> 5) + kb0, nb = kbN - kb0;
;     asm volatile("s_waitcnt vmcnt(0) lgkmcnt(0)" ::: "memory");
;     kv_dma(Kp, Vp, blk0, ring);
;     kv_dma(Kp, Vp, blk0 + 1, ring + 8192);
;     bf16x8 qf[2][4];
; #pragma unroll
;     for (int qb = 0; qb < 2; ++qb)
; #pragma unroll
;         for (int ds = 0; ds < 4; ++ds) qf[qb][ds] = *(const bf16x8*)(Qp + (qb < nq ? 32 * qb + r : r) * 64 + 16 * ds + 8 * hh);
;     f32x16 o[2][2];
; #pragma unroll
;     for (int a = 0; a < 2; ++a)
; #pragma unroll
;         for (int b = 0; b < 2; ++b)
; #pragma unroll
;             for (int i = 0; i < 16; ++i) o[a][b][i] = 0.f;
;     float mrun[2], lrun[2];
; #pragma unroll
;     for (int a = 0; a < 2; ++a) {
;         if (ISB) { mrun[a] = sinks[hq] * LOG2E; lrun[a] = hh ? 0.f : 1.f; }
;         else { mrun[a] = -1e30f; lrun[a] = 0.f; } }
;     const LAS float* biasR = biasL + hq * 256;
;     const float bconst = ISB ? 0.f : biasR[0];
;     asm volatile("s_waitcnt vmcnt(0)" ::: "memory");
.LBB0_615:
	s_ashr_i32 s1, s6, 31
	s_add_u32 s0, s33, s6
	s_addc_u32 s1, 0, s1
	s_lshl_b64 s[26:27], s[0:1], 7
	s_ashr_i32 s0, s4, 5
	s_add_i32 s0, s0, s7
	s_mov_b32 s28, s0
	s_mov_b32 s92, s7
	s_ashr_i32 s1, s0, 31
	s_lshl_b64 s[4:5], s[0:1], 12
	s_mov_b32 m0, s31
	s_waitcnt lgkmcnt(0)
	v_lshl_add_u64 v[0:1], v[162:163], 0, s[4:5]
	global_load_lds_dwordx4 v[0:1], off
	v_lshl_add_u64 v[2:3], v[0:1], 0, s[16:17]
	s_mov_b32 m0, s43
	s_nop 0
	global_load_lds_dwordx4 v[2:3], off
	v_lshl_add_u64 v[2:3], v[0:1], 0, s[18:19]
	s_mov_b32 m0, s44
	v_lshl_add_u64 v[0:1], v[0:1], 0, s[20:21]
	global_load_lds_dwordx4 v[2:3], off
	s_mov_b32 m0, s45
	s_nop 0
	global_load_lds_dwordx4 v[0:1], off
	v_lshl_add_u64 v[0:1], v[164:165], 0, s[4:5]
	s_mov_b32 m0, s46
	v_lshl_add_u64 v[2:3], v[0:1], 0, s[16:17]
	global_load_lds_dwordx4 v[0:1], off
	s_mov_b32 m0, s47
	s_add_u32 s4, s4, 0x1000
	global_load_lds_dwordx4 v[2:3], off
	v_lshl_add_u64 v[2:3], v[0:1], 0, s[18:19]
	s_mov_b32 m0, s48
	v_lshl_add_u64 v[0:1], v[0:1], 0, s[20:21]
	global_load_lds_dwordx4 v[2:3], off
	s_mov_b32 m0, s49
	s_addc_u32 s5, s5, 0
	global_load_lds_dwordx4 v[0:1], off
	v_lshl_add_u64 v[0:1], v[162:163], 0, s[4:5]
	s_mov_b32 m0, s50
	v_lshl_add_u64 v[2:3], v[0:1], 0, s[16:17]
	global_load_lds_dwordx4 v[0:1], off
	s_mov_b32 m0, s51
	s_cmp_lt_u32 s7, 6
	global_load_lds_dwordx4 v[2:3], off
	v_lshl_add_u64 v[2:3], v[0:1], 0, s[18:19]
	s_mov_b32 m0, s52
	v_lshl_add_u64 v[0:1], v[0:1], 0, s[20:21]
	global_load_lds_dwordx4 v[2:3], off
	s_mov_b32 m0, s53
	s_nop 0
	global_load_lds_dwordx4 v[0:1], off
	v_lshl_add_u64 v[0:1], v[164:165], 0, s[4:5]
	s_mov_b32 m0, s54
	v_lshl_add_u64 v[2:3], v[0:1], 0, s[16:17]
	global_load_lds_dwordx4 v[0:1], off
	s_mov_b32 m0, s55
	s_mov_b64 s[4:5], -1
	global_load_lds_dwordx4 v[2:3], off
	v_lshl_add_u64 v[2:3], v[0:1], 0, s[18:19]
	s_mov_b32 m0, s56
	v_lshl_add_u64 v[0:1], v[0:1], 0, s[20:21]
	global_load_lds_dwordx4 v[2:3], off
	s_mov_b32 m0, s57
	s_nop 0
	global_load_lds_dwordx4 v[0:1], off
	v_lshl_add_u64 v[0:1], v[166:167], 0, s[26:27]
	global_load_dwordx4 v[96:99], v[0:1], off
	global_load_dwordx4 v[100:103], v[0:1], off offset:32
	global_load_dwordx4 v[104:107], v[0:1], off offset:64
	global_load_dwordx4 v[108:111], v[0:1], off offset:96
	v_add_co_u32_e32 v0, vcc, 0x1000, v0
	s_nop 1
	v_addc_co_u32_e32 v1, vcc, 0, v1, vcc
	global_load_dwordx4 v[112:115], v[0:1], off
	global_load_dwordx4 v[116:119], v[0:1], off offset:32
	global_load_dwordx4 v[120:123], v[0:1], off offset:64
	global_load_dwordx4 v[124:127], v[0:1], off offset:96
	global_load_dword v66, v161, s[14:15]
	s_waitcnt vmcnt(0)
	s_cbranch_scc1 .LBB0_617
	v_and_b32_e32 v0, 64, v186
	v_xor_b32_e32 v156, 32, v186
	v_add_u32_e32 v157, 64, v0
	s_mov_b64 s[4:5], 0
.LBB0_617:
	v_mov_b32_e32 v47, 0
	s_andn2_b64 vcc, exec, s[4:5]
	v_mov_b32_e32 v46, 0
	v_mov_b32_e32 v45, 0
	v_mov_b32_e32 v44, 0
	v_mov_b32_e32 v43, 0
	v_mov_b32_e32 v42, 0
	v_mov_b32_e32 v41, 0
	v_mov_b32_e32 v40, 0
	v_mov_b32_e32 v39, 0
	v_mov_b32_e32 v38, 0
	v_mov_b32_e32 v37, 0
	v_mov_b32_e32 v36, 0
	v_mov_b32_e32 v35, 0
	v_mov_b32_e32 v34, 0
	v_mov_b32_e32 v33, 0
	v_mov_b32_e32 v32, 0
	v_mov_b32_e32 v15, 0
	v_mov_b32_e32 v14, 0
	v_mov_b32_e32 v13, 0
	v_mov_b32_e32 v12, 0
	v_mov_b32_e32 v11, 0
	v_mov_b32_e32 v10, 0
	v_mov_b32_e32 v9, 0
	v_mov_b32_e32 v8, 0
	v_mov_b32_e32 v7, 0
	v_mov_b32_e32 v6, 0
	v_mov_b32_e32 v5, 0
	v_mov_b32_e32 v4, 0
	v_mov_b32_e32 v3, 0
	v_mov_b32_e32 v2, 0
	v_mov_b32_e32 v1, 0
	v_mov_b32_e32 v0, 0
	v_mov_b32_e32 v63, 0
	v_mov_b32_e32 v62, 0
	v_mov_b32_e32 v61, 0
	v_mov_b32_e32 v60, 0
	v_mov_b32_e32 v59, 0
	v_mov_b32_e32 v58, 0
	v_mov_b32_e32 v57, 0
	v_mov_b32_e32 v56, 0
	v_mov_b32_e32 v55, 0
	v_mov_b32_e32 v54, 0
	v_mov_b32_e32 v53, 0
	v_mov_b32_e32 v52, 0
	v_mov_b32_e32 v51, 0
	v_mov_b32_e32 v50, 0
	v_mov_b32_e32 v49, 0
	v_mov_b32_e32 v48, 0
	v_mov_b32_e32 v31, 0
	v_mov_b32_e32 v30, 0
	v_mov_b32_e32 v29, 0
	v_mov_b32_e32 v28, 0
	v_mov_b32_e32 v27, 0
	v_mov_b32_e32 v26, 0
	v_mov_b32_e32 v25, 0
	v_mov_b32_e32 v24, 0
	v_mov_b32_e32 v23, 0
	v_mov_b32_e32 v22, 0
	v_mov_b32_e32 v21, 0
	v_mov_b32_e32 v20, 0
	v_mov_b32_e32 v19, 0
	v_mov_b32_e32 v18, 0
	v_mov_b32_e32 v17, 0
	v_mov_b32_e32 v16, 0
	v_mov_b32_e32 v181, v183
	v_mov_b32_e32 v179, v183
	v_mov_b32_e32 v176, v186
	s_cbranch_vccnz .LBB0_641
	v_mov_b64_e32 v[32:33], 0
	v_mov_b64_e32 v[34:35], 0
	v_mov_b64_e32 v[36:37], 0
	v_mov_b64_e32 v[38:39], 0
	v_mov_b64_e32 v[40:41], 0
	v_mov_b64_e32 v[42:43], 0
	v_mov_b64_e32 v[44:45], 0
	v_mov_b64_e32 v[46:47], 0
	v_mov_b64_e32 v[0:1], 0
	v_mov_b64_e32 v[2:3], 0
	v_mov_b64_e32 v[4:5], 0
	v_mov_b64_e32 v[6:7], 0
	v_mov_b64_e32 v[8:9], 0
	v_mov_b64_e32 v[10:11], 0
	v_mov_b64_e32 v[12:13], 0
	v_mov_b64_e32 v[14:15], 0
	v_mov_b64_e32 v[48:49], 0
	v_mov_b64_e32 v[50:51], 0
	v_mov_b64_e32 v[52:53], 0
	v_mov_b64_e32 v[54:55], 0
	v_mov_b64_e32 v[56:57], 0
	v_mov_b64_e32 v[58:59], 0
	v_mov_b64_e32 v[60:61], 0
	v_mov_b64_e32 v[62:63], 0
	v_mov_b64_e32 v[16:17], 0
	v_mov_b64_e32 v[18:19], 0
	v_mov_b64_e32 v[20:21], 0
	v_mov_b64_e32 v[22:23], 0
	v_mov_b64_e32 v[24:25], 0
	v_mov_b64_e32 v[26:27], 0
	v_mov_b64_e32 v[28:29], 0
	v_mov_b64_e32 v[30:31], 0
	v_mul_f32_e32 v244, 0x3fb8aa3b, v66
	v_mov_b32_e32 v181, v183
	v_mov_b32_e32 v179, v183
	v_mov_b32_e32 v245, v244
	s_sub_i32 s94, 6, s92
	s_mov_b32 s29, 0
	s_mov_b32 s95, s92
	s_mov_b32 s96, s31
	v_add_u32_e32 v147, s31, v158
	v_readfirstlane_b32 s0, v162
	v_readfirstlane_b32 s1, v163
	v_readfirstlane_b32 s4, v164
	v_readfirstlane_b32 s5, v165
	s_add_i32 s7, s28, 2
	s_lshl_b32 s7, s7, 12
	s_add_u32 s0, s0, s7
	s_addc_u32 s1, s1, 0
	s_add_u32 s4, s4, s7
	s_addc_u32 s5, s5, 0
	ds_read_b128 v[130:133], v147
	ds_read_b128 v[134:137], v147 offset:1024
	ds_read_b128 v[138:141], v147 offset:2048
	ds_read_b128 v[142:145], v147 offset:3072
; #define LAS __attribute__((address_space(3)))
; #define MFMA32(a, b, c) __builtin_amdgcn_mfma_f32_32x32x16_bf16((a), (b), (c), 0, 0, 0)
; template <bool ISB>
; DI void attn_block(const LAS unsigned char* slot, const bf16x8 (&qf)[2][4], f32x16 (&o)[2][2], float (&mrun)[2], float (&lrun)[2], int kb, int r, int hh, int lane, const LAS float* biasR, float bconst, int qoff, int nq) {
;     ...
;     for (int qb = 0; qb < 2; ++qb) {
;         if (qb >= nq) continue;
;         f32x16 s;
; #pragma unroll
;         for (int i = 0; i < 16; ++i) s[i] = 0.f;
; #pragma unroll
;         for (int ds = 0; ds < 4; ++ds) s = MFMA32(kf[ds], qf[qb][ds], s);
;         float cadd = 0.f;
;         if (!ISB) {
;             if (kb >= 12) {
;                 const LAS float* bp = biasR + (191 - (512 + qoff + 32 * qb + r - 32 * kb - 4 * hh));
; #pragma unroll
;                 for (int i = 0; i < 16; ++i) s[i] += bp[8 * (i >> 2) + (i & 3)];
;             } else cadd = bconst;
;         }
;         float mx = fmaxf(fmaxf(s[0], s[1]), s[2]);
; #pragma unroll
;         for (int i = 3; i < 15; i += 2) mx = fmaxf(fmaxf(mx, s[i]), s[i + 1]);
;         mx = fmaxf(mx, s[15]);
;         mx = fmaxf(mx, __shfl_xor(mx, 32)) + cadd;
;         if (__any(mx > mrun[qb] + 8.f)) {
;             const float mnew = fmaxf(mrun[qb], mx), alpha = __builtin_amdgcn_exp2f(mrun[qb] - mnew);
;             mrun[qb] = mnew; lrun[qb] *= alpha;
; #pragma unroll
;             for (int i = 0; i < 16; ++i) { o[qb][0][i] *= alpha; o[qb][1][i] *= alpha; }
;         }
.Lat_b_top_q2:
	ds_read_b128 v[194:197], v147 offset:4096
	ds_read_b128 v[198:201], v147 offset:5120
	ds_read_b128 v[202:205], v147 offset:6144
	ds_read_b128 v[206:209], v147 offset:7168
	s_waitcnt lgkmcnt(4)
	v_mfma_f32_32x32x16_bf16 v[64:79], v[130:133], v[96:99], 0
	v_mfma_f32_32x32x16_bf16 v[64:79], v[134:137], v[100:103], v[64:79]
	v_mfma_f32_32x32x16_bf16 v[64:79], v[138:141], v[104:107], v[64:79]
	v_mfma_f32_32x32x16_bf16 v[64:79], v[142:145], v[108:111], v[64:79]
	v_mfma_f32_32x32x16_bf16 v[80:95], v[130:133], v[112:115], 0
	v_mfma_f32_32x32x16_bf16 v[80:95], v[134:137], v[116:119], v[80:95]
	v_mfma_f32_32x32x16_bf16 v[80:95], v[138:141], v[120:123], v[80:95]
	v_mfma_f32_32x32x16_bf16 v[80:95], v[142:145], v[124:127], v[80:95]
	s_nop 7
	v_max3_f32 v246, v64, v65, v66
	v_max3_f32 v246, v246, v67, v68
	v_max3_f32 v246, v246, v69, v70
	v_max3_f32 v246, v246, v71, v72
	v_max3_f32 v246, v246, v73, v74
	v_max3_f32 v246, v246, v75, v76
	v_max3_f32 v246, v246, v77, v78
	v_max_f32_e32 v246, v246, v79
	v_max3_f32 v247, v80, v81, v82
	v_max3_f32 v247, v247, v83, v84
	v_max3_f32 v247, v247, v85, v86
	v_max3_f32 v247, v247, v87, v88
	v_max3_f32 v247, v247, v89, v90
	v_max3_f32 v247, v247, v91, v92
	v_max3_f32 v247, v247, v93, v94
	v_max_f32_e32 v247, v247, v95
	v_mov_b32_e32 v248, v246
	v_mov_b32_e32 v249, v247
	s_nop 0
	v_permlane32_swap_b32_e32 v248, v246
	v_permlane32_swap_b32_e32 v249, v247
	v_max_f32_e32 v246, v246, v248
	v_max_f32_e32 v247, v247, v249
	v_mov_b32_e32 v153, v246
	v_add_f32_e32 v248, v244, v177
	v_mov_b32_e32 v154, v247
	v_add_f32_e32 v249, v245, v177
	v_cmp_gt_f32_e32 vcc, v153, v248
	s_cbranch_vccz .Lat_b_nors0_q2
	v_max_f32_e32 v248, v244, v153
	v_sub_f32_e32 v151, v244, v248
	v_exp_f32_e32 v151, v151
	v_mov_b32_e32 v244, v248
	s_nop 0
	v_mul_f32_e32 v181, v181, v151
	v_mul_f32_e32 v32, v32, v151
	v_mul_f32_e32 v33, v33, v151
	v_mul_f32_e32 v34, v34, v151
	v_mul_f32_e32 v35, v35, v151
	v_mul_f32_e32 v36, v36, v151
	v_mul_f32_e32 v37, v37, v151
	v_mul_f32_e32 v38, v38, v151
	v_mul_f32_e32 v39, v39, v151
	v_mul_f32_e32 v40, v40, v151
	v_mul_f32_e32 v41, v41, v151
	v_mul_f32_e32 v42, v42, v151
	v_mul_f32_e32 v43, v43, v151
	v_mul_f32_e32 v44, v44, v151
	v_mul_f32_e32 v45, v45, v151
	v_mul_f32_e32 v46, v46, v151
	v_mul_f32_e32 v47, v47, v151
	v_mul_f32_e32 v0, v0, v151
	v_mul_f32_e32 v1, v1, v151
	v_mul_f32_e32 v2, v2, v151
	v_mul_f32_e32 v3, v3, v151
	v_mul_f32_e32 v4, v4, v151
	v_mul_f32_e32 v5, v5, v151
	v_mul_f32_e32 v6, v6, v151
	v_mul_f32_e32 v7, v7, v151
	v_mul_f32_e32 v8, v8, v151
	v_mul_f32_e32 v9, v9, v151
	v_mul_f32_e32 v10, v10, v151
	v_mul_f32_e32 v11, v11, v151
	v_mul_f32_e32 v12, v12, v151
	v_mul_f32_e32 v13, v13, v151
	v_mul_f32_e32 v14, v14, v151
	v_mul_f32_e32 v15, v15, v151
.Lat_b_nors0_q2:
	v_cmp_gt_f32_e32 vcc, v154, v249
	s_cbranch_vccz .Lat_b_nors1_q2
	v_max_f32_e32 v249, v245, v154
	v_sub_f32_e32 v152, v245, v249
	v_exp_f32_e32 v152, v152
	v_mov_b32_e32 v245, v249
	s_nop 0
	v_mul_f32_e32 v179, v179, v152
	v_mul_f32_e32 v48, v48, v152
	v_mul_f32_e32 v49, v49, v152
	v_mul_f32_e32 v50, v50, v152
	v_mul_f32_e32 v51, v51, v152
	v_mul_f32_e32 v52, v52, v152
	v_mul_f32_e32 v53, v53, v152
	v_mul_f32_e32 v54, v54, v152
	v_mul_f32_e32 v55, v55, v152
	v_mul_f32_e32 v56, v56, v152
	v_mul_f32_e32 v57, v57, v152
	v_mul_f32_e32 v58, v58, v152
	v_mul_f32_e32 v59, v59, v152
	v_mul_f32_e32 v60, v60, v152
	v_mul_f32_e32 v61, v61, v152
	v_mul_f32_e32 v62, v62, v152
	v_mul_f32_e32 v63, v63, v152
	v_mul_f32_e32 v16, v16, v152
	v_mul_f32_e32 v17, v17, v152
	v_mul_f32_e32 v18, v18, v152
	v_mul_f32_e32 v19, v19, v152
	v_mul_f32_e32 v20, v20, v152
	v_mul_f32_e32 v21, v21, v152
	v_mul_f32_e32 v22, v22, v152
	v_mul_f32_e32 v23, v23, v152
	v_mul_f32_e32 v24, v24, v152
	v_mul_f32_e32 v25, v25, v152
	v_mul_f32_e32 v26, v26, v152
	v_mul_f32_e32 v27, v27, v152
	v_mul_f32_e32 v28, v28, v152
	v_mul_f32_e32 v29, v29, v152
	v_mul_f32_e32 v30, v30, v152
	v_mul_f32_e32 v31, v31, v152
; #define LAS __attribute__((address_space(3)))
; #define MFMA32(a, b, c) __builtin_amdgcn_mfma_f32_32x32x16_bf16((a), (b), (c), 0, 0, 0)
; template <bool ISB>
; DI void attn_block(const LAS unsigned char* slot, const bf16x8 (&qf)[2][4], f32x16 (&o)[2][2], float (&mrun)[2], float (&lrun)[2], int kb, int r, int hh, int lane, const LAS float* biasR, float bconst, int qoff, int nq) {
;     ...
;         const float c = cadd - mrun[qb];
;         float psum = 0.f;
; #pragma unroll
;         for (int i = 0; i < 16; ++i) { s[i] = __builtin_amdgcn_exp2f(s[i] + c); psum += s[i]; }
;         lrun[qb] += psum;
;         bf16x8 pf[2];
; #pragma unroll
;         for (int t = 0; t < 2; ++t) { u32x4 p; p.x = pk2(s[8 * t], s[8 * t + 1]); p.y = pk2(s[8 * t + 2], s[8 * t + 3]); p.z = pk2(s[8 * t + 4], s[8 * t + 5]); p.w = pk2(s[8 * t + 6], s[8 * t + 7]);
;             pf[t] = __builtin_bit_cast(bf16x8, p); }
; #pragma unroll
;         for (int db = 0; db < 2; ++db)
; #pragma unroll
;             for (int t = 0; t < 2; ++t) o[qb][db] = MFMA32(vf[db][t], pf[t], o[qb][db]);
; template <bool ISB>
; DI void attn_unit(int u, int hq, int qoff, int nq, const bf16_t* Qb, const bf16_t* Kb, const bf16_t* Vtb, bf16_t* O, const float* sinks, const LAS float* biasL, LAS unsigned char* ring, int lane) {
;     ...
;     for (int ib = 0; ib < nb; ++ib) {
;         LAS unsigned char* slot = ring + (ib & 1) * 8192;
;         if (ib >= 2) { if (ib + 1 < nb) asm volatile("s_waitcnt vmcnt(8)" ::: "memory"); else asm volatile("s_waitcnt vmcnt(0)" ::: "memory"); }
;         attn_block<ISB>(slot, qf, o, mrun, lrun, kb0 + ib, r, hh, lane, biasR, bconst, qoff, nq);
;         if (ib + 2 < nb) { asm volatile("s_waitcnt lgkmcnt(0)" ::: "memory"); __builtin_amdgcn_sched_barrier(0); kv_dma(Kp, Vp, blk0 + ib + 2, slot); }
;     }
.Lat_b_nors1_q2:
	v_sub_f32_e32 v250, 0, v244
	v_sub_f32_e32 v251, 0, v245
	v_add_f32_e32 v64, v64, v250
	v_exp_f32_e32 v210, v64
	v_add_f32_e32 v65, v65, v250
	v_exp_f32_e32 v211, v65
	v_add_f32_e32 v66, v66, v250
	v_exp_f32_e32 v212, v66
	v_add_f32_e32 v67, v67, v250
	v_exp_f32_e32 v213, v67
	v_add_f32_e32 v68, v68, v250
	v_exp_f32_e32 v214, v68
	v_add_f32_e32 v69, v69, v250
	v_exp_f32_e32 v215, v69
	v_add_f32_e32 v70, v70, v250
	v_exp_f32_e32 v216, v70
	v_add_f32_e32 v71, v71, v250
	v_exp_f32_e32 v217, v71
	v_add_f32_e32 v72, v72, v250
	v_exp_f32_e32 v218, v72
	v_add_f32_e32 v73, v73, v250
	v_exp_f32_e32 v219, v73
	v_add_f32_e32 v74, v74, v250
	v_exp_f32_e32 v220, v74
	v_add_f32_e32 v75, v75, v250
	v_exp_f32_e32 v221, v75
	v_add_f32_e32 v76, v76, v250
	v_exp_f32_e32 v222, v76
	v_add_f32_e32 v77, v77, v250
	v_exp_f32_e32 v223, v77
	v_add_f32_e32 v78, v78, v250
	v_exp_f32_e32 v224, v78
	v_add_f32_e32 v79, v79, v250
	v_exp_f32_e32 v225, v79
	v_cvt_pk_bf16_f32 v64, v210, v211
	v_cvt_pk_bf16_f32 v65, v212, v213
	v_cvt_pk_bf16_f32 v66, v214, v215
	v_cvt_pk_bf16_f32 v67, v216, v217
	v_cvt_pk_bf16_f32 v68, v218, v219
	v_cvt_pk_bf16_f32 v69, v220, v221
	v_cvt_pk_bf16_f32 v70, v222, v223
	v_cvt_pk_bf16_f32 v71, v224, v225
	s_waitcnt lgkmcnt(0)
	s_nop 0
	v_mfma_f32_32x32x16_bf16 v[32:47], v[194:197], v[64:67], v[32:47]
	v_add_f32_e32 v80, v80, v251
	v_exp_f32_e32 v228, v80
	v_add_f32_e32 v81, v81, v251
	v_exp_f32_e32 v229, v81
	v_add_f32_e32 v82, v82, v251
	v_exp_f32_e32 v230, v82
	v_add_f32_e32 v83, v83, v251
	v_exp_f32_e32 v231, v83
	v_mfma_f32_32x32x16_bf16 v[0:15], v[202:205], v[64:67], v[0:15]
	v_add_f32_e32 v84, v84, v251
	v_exp_f32_e32 v232, v84
	v_add_f32_e32 v85, v85, v251
	v_exp_f32_e32 v233, v85
	v_add_f32_e32 v86, v86, v251
	v_exp_f32_e32 v234, v86
	v_add_f32_e32 v87, v87, v251
	v_exp_f32_e32 v235, v87
	v_mfma_f32_32x32x16_bf16 v[32:47], v[198:201], v[68:71], v[32:47]
	v_add_f32_e32 v88, v88, v251
	v_exp_f32_e32 v236, v88
	v_add_f32_e32 v89, v89, v251
	v_exp_f32_e32 v237, v89
	v_add_f32_e32 v90, v90, v251
	v_exp_f32_e32 v238, v90
	v_add_f32_e32 v91, v91, v251
	v_exp_f32_e32 v239, v91
	v_mfma_f32_32x32x16_bf16 v[0:15], v[206:209], v[68:71], v[0:15]
	v_add_f32_e32 v92, v92, v251
	v_exp_f32_e32 v240, v92
	v_add_f32_e32 v93, v93, v251
	v_exp_f32_e32 v241, v93
	v_add_f32_e32 v94, v94, v251
	v_exp_f32_e32 v242, v94
	v_add_f32_e32 v95, v95, v251
	v_exp_f32_e32 v243, v95
	v_cvt_pk_bf16_f32 v80, v228, v229
	v_cvt_pk_bf16_f32 v81, v230, v231
	v_cvt_pk_bf16_f32 v82, v232, v233
	v_cvt_pk_bf16_f32 v83, v234, v235
	v_cvt_pk_bf16_f32 v84, v236, v237
	v_cvt_pk_bf16_f32 v85, v238, v239
	v_cvt_pk_bf16_f32 v86, v240, v241
	v_cvt_pk_bf16_f32 v87, v242, v243
	s_nop 1
	v_mfma_f32_32x32x16_bf16 v[48:63], v[194:197], v[80:83], v[48:63]
	v_mov_b32_e32 v151, 0
	v_mov_b32_e32 v152, 0
	v_add_f32_e32 v151, v151, v210
	v_add_f32_e32 v152, v152, v228
	v_add_f32_e32 v151, v151, v211
	v_add_f32_e32 v152, v152, v229
	v_add_f32_e32 v151, v151, v212
	v_add_f32_e32 v152, v152, v230
	v_add_f32_e32 v151, v151, v213
	v_mfma_f32_32x32x16_bf16 v[16:31], v[202:205], v[80:83], v[16:31]
	v_add_f32_e32 v152, v152, v231
	v_add_f32_e32 v151, v151, v214
	v_add_f32_e32 v152, v152, v232
	v_add_f32_e32 v151, v151, v215
	v_add_f32_e32 v152, v152, v233
	v_add_f32_e32 v151, v151, v216
	v_add_f32_e32 v152, v152, v234
	v_add_f32_e32 v151, v151, v217
	v_add_f32_e32 v152, v152, v235
	v_mfma_f32_32x32x16_bf16 v[48:63], v[198:201], v[84:87], v[48:63]
	v_add_f32_e32 v151, v151, v218
	v_add_f32_e32 v152, v152, v236
	v_add_f32_e32 v151, v151, v219
	v_add_f32_e32 v152, v152, v237
	v_add_f32_e32 v151, v151, v220
	v_add_f32_e32 v152, v152, v238
	v_add_f32_e32 v151, v151, v221
	v_add_f32_e32 v152, v152, v239
	v_add_f32_e32 v151, v151, v222
	v_mfma_f32_32x32x16_bf16 v[16:31], v[206:209], v[84:87], v[16:31]
	v_add_f32_e32 v152, v152, v240
	v_add_f32_e32 v151, v151, v223
	v_add_f32_e32 v152, v152, v241
	v_add_f32_e32 v151, v151, v224
	v_add_f32_e32 v152, v152, v242
	v_add_f32_e32 v151, v151, v225
	v_add_f32_e32 v152, v152, v243
	v_add_f32_e32 v181, v181, v151
	v_add_f32_e32 v179, v179, v152
	s_add_i32 s29, s29, 1
	s_add_i32 s7, s29, 1
	s_cmp_ge_u32 s7, s94
	s_cbranch_scc1 .Lat_b_nodma_q2
	s_mov_b32 m0, s96
	s_nop 0
	global_load_lds_dwordx4 v158, s[0:1]
	global_load_lds_dwordx4 v158, s[0:1] offset:1024
	global_load_lds_dwordx4 v158, s[0:1] offset:2048
	global_load_lds_dwordx4 v158, s[0:1] offset:3072
	s_add_i32 m0, s96, 0x1000
	s_add_u32 s0, s0, 0x1000
	s_addc_u32 s1, s1, 0
	global_load_lds_dwordx4 v158, s[4:5]
	global_load_lds_dwordx4 v158, s[4:5] offset:1024
	global_load_lds_dwordx4 v158, s[4:5] offset:2048
	global_load_lds_dwordx4 v158, s[4:5] offset:3072
	s_add_u32 s4, s4, 0x1000
	s_addc_u32 s5, s5, 0
	s_waitcnt vmcnt(8)
	s_branch .Lat_b_kpre_q2
.Lat_b_nodma_q2:
	s_cmp_ge_u32 s29, s94
	s_cbranch_scc1 .Lat_b_done
	s_waitcnt vmcnt(0)
.Lat_b_kpre_q2:
	s_xor_b32 s96, s96, 0x2000
	v_xor_b32_e32 v147, 0x2000, v147
	s_add_i32 s95, s95, 1
	ds_read_b128 v[130:133], v147
	ds_read_b128 v[134:137], v147 offset:1024
	ds_read_b128 v[138:141], v147 offset:2048
	ds_read_b128 v[142:145], v147 offset:3072
	s_branch .Lat_b_top_q2
.Lat_b_done:
	v_mbcnt_hi_u32_b32 v176, -1, v185
	v_and_b32_e32 v157, 64, v176
	v_xor_b32_e32 v156, 32, v176
	v_add_u32_e32 v157, 64, v157
	s_branch .LBB0_641

; #define LAS __attribute__((address_space(3)))
; template <bool ISB>
; DI void attn_unit(int u, int hq, int qoff, int nq, const bf16_t* Qb, const bf16_t* Kb, const bf16_t* Vtb, bf16_t* O, const float* sinks, const LAS float* biasL, LAS unsigned char* ring, int lane) {
;     ...
;     if (u < 256) { kbase = 64 * (u - (NCH - 1)); j0 = (NCH - 1) - u; if (j0 < 0) j0 = 0; } else { kbase = SEQ + (u - 256) * (64 * NCH); j0 = 0; }
;     const bf16_t* Qp = Qb + ((size_t)hq * MTOK + 64 * u + qoff) * 64;
;     const bf16_t* Kp = Kb + (size_t)hk * KROWS * 64 + 8 * lane;
;     const bf16_t* Vp = Vtb + (size_t)hk * KROWS * 64 + 8 * lane;
;     const int kb0 = 2 * j0, kbN = 2 * NCH, blk0 = (kbase >> 5) + kb0, nb = kbN - kb0;
;     asm volatile("s_waitcnt vmcnt(0) lgkmcnt(0)" ::: "memory");
;     kv_dma(Kp, Vp, blk0, ring);
;     kv_dma(Kp, Vp, blk0 + 1, ring + 8192);
;     bf16x8 qf[2][4];
; #pragma unroll
;     for (int qb = 0; qb < 2; ++qb)
; #pragma unroll
;         for (int ds = 0; ds < 4; ++ds) qf[qb][ds] = *(const bf16x8*)(Qp + (qb < nq ? 32 * qb + r : r) * 64 + 16 * ds + 8 * hh);
;     f32x16 o[2][2];
; #pragma unroll
;     for (int a = 0; a < 2; ++a)
; #pragma unroll
;         for (int b = 0; b < 2; ++b)
; #pragma unroll
;             for (int i = 0; i < 16; ++i) o[a][b][i] = 0.f;
;     float mrun[2], lrun[2];
; #pragma unroll
;     for (int a = 0; a < 2; ++a) {
;         if (ISB) { mrun[a] = sinks[hq] * LOG2E; lrun[a] = hh ? 0.f : 1.f; }
;         else { mrun[a] = -1e30f; lrun[a] = 0.f; } }
;     const LAS float* biasR = biasL + hq * 256;
;     const float bconst = ISB ? 0.f : biasR[0];
;     asm volatile("s_waitcnt vmcnt(0)" ::: "memory");
.LBB0_647:
	s_cmp_eq_u32 s12, 9
	s_cselect_b32 s93, 32, 0
	s_ashr_i32 s0, s91, 31
	s_add_u32 s5, s33, s91
	s_addc_u32 s1, 0, s0
	s_ashr_i32 s4, s4, 5
	s_add_i32 s28, s4, s92
	s_ashr_i32 s29, s28, 31
	s_or_b32 s0, s5, s93
	s_lshl_b64 s[4:5], s[28:29], 12
	s_mov_b32 m0, s31
	s_waitcnt lgkmcnt(0)
	v_lshl_add_u64 v[0:1], v[168:169], 0, s[4:5]
	global_load_lds_dwordx4 v[0:1], off
	v_lshl_add_u64 v[2:3], v[0:1], 0, s[16:17]
	s_mov_b32 m0, s43
	s_lshl_b64 s[0:1], s[0:1], 7
	global_load_lds_dwordx4 v[2:3], off
	v_lshl_add_u64 v[2:3], v[0:1], 0, s[18:19]
	s_mov_b32 m0, s44
	v_lshl_add_u64 v[0:1], v[0:1], 0, s[20:21]
	global_load_lds_dwordx4 v[2:3], off
	s_mov_b32 m0, s45
	s_add_u32 s6, s4, 0x1000
	global_load_lds_dwordx4 v[0:1], off
	v_lshl_add_u64 v[0:1], v[170:171], 0, s[4:5]
	s_mov_b32 m0, s46
	v_lshl_add_u64 v[2:3], v[0:1], 0, s[16:17]
	global_load_lds_dwordx4 v[0:1], off
	s_mov_b32 m0, s47
	s_addc_u32 s7, s5, 0
	global_load_lds_dwordx4 v[2:3], off
	v_lshl_add_u64 v[2:3], v[0:1], 0, s[18:19]
	s_mov_b32 m0, s48
	v_lshl_add_u64 v[0:1], v[0:1], 0, s[20:21]
	global_load_lds_dwordx4 v[2:3], off
	s_mov_b32 m0, s49
	s_cmp_lt_u32 s12, 8
	global_load_lds_dwordx4 v[0:1], off
	v_lshl_add_u64 v[0:1], v[168:169], 0, s[6:7]
	s_mov_b32 m0, s50
	v_lshl_add_u64 v[2:3], v[0:1], 0, s[16:17]
	global_load_lds_dwordx4 v[0:1], off
	s_mov_b32 m0, s51
	s_waitcnt lgkmcnt(0)
	s_cselect_b64 s[26:27], -1, 0
	global_load_lds_dwordx4 v[2:3], off
	v_lshl_add_u64 v[2:3], v[0:1], 0, s[18:19]
	s_mov_b32 m0, s52
	v_lshl_add_u64 v[0:1], v[0:1], 0, s[20:21]
	global_load_lds_dwordx4 v[2:3], off
	s_mov_b32 m0, s53
	s_nop 0
	global_load_lds_dwordx4 v[0:1], off
	v_lshl_add_u64 v[0:1], v[170:171], 0, s[6:7]
	s_mov_b32 m0, s54
	v_lshl_add_u64 v[2:3], v[0:1], 0, s[16:17]
	global_load_lds_dwordx4 v[0:1], off
	s_mov_b32 m0, s55
	s_nop 0
	global_load_lds_dwordx4 v[2:3], off
	v_lshl_add_u64 v[2:3], v[0:1], 0, s[18:19]
	s_mov_b32 m0, s56
	v_lshl_add_u64 v[0:1], v[0:1], 0, s[20:21]
	global_load_lds_dwordx4 v[2:3], off
	s_mov_b32 m0, s57
	s_nop 0
	global_load_lds_dwordx4 v[0:1], off
	v_lshl_add_u64 v[0:1], v[172:173], 0, s[0:1]
	s_and_b64 s[0:1], s[26:27], exec
	v_lshl_add_u64 v[2:3], v[0:1], 0, v[160:161]
	s_cselect_b32 s0, 32, 0
	global_load_dwordx4 v[98:101], v[2:3], off
	global_load_dwordx4 v[102:105], v[2:3], off offset:32
	global_load_dwordx4 v[106:109], v[2:3], off offset:64
	global_load_dwordx4 v[110:113], v[2:3], off offset:96
	v_or_b32_e32 v2, s0, v182
	v_lshlrev_b32_e32 v2, 7, v2
	v_mov_b32_e32 v3, v161
	v_lshl_add_u64 v[0:1], v[0:1], 0, v[2:3]
	global_load_dwordx4 v[114:117], v[0:1], off
	global_load_dwordx4 v[118:121], v[0:1], off offset:32
	global_load_dwordx4 v[122:125], v[0:1], off offset:64
	global_load_dwordx4 v[126:129], v[0:1], off offset:96
	v_mov_b32_e32 v0, s34
	ds_read_b32 v189, v0
	s_waitcnt vmcnt(0)
	s_cmp_lt_u32 s92, 18
	s_mov_b64 s[0:1], -1
	s_cbranch_scc1 .LBB0_649
	v_mbcnt_hi_u32_b32 v191, -1, v185
	v_and_b32_e32 v0, 64, v191
	v_xor_b32_e32 v192, 32, v191
	v_add_u32_e32 v193, 64, v0
	s_mov_b64 s[0:1], 0
.LBB0_649:
	s_andn2_b64 vcc, exec, s[0:1]
	v_or_b32_e32 v188, s93, v182
	s_cbranch_vccnz .LBB0_652
	v_mov_b64_e32 v[16:17], 0
	v_mov_b64_e32 v[18:19], 0
	v_mov_b64_e32 v[20:21], 0
	v_mov_b64_e32 v[22:23], 0
	v_mov_b64_e32 v[24:25], 0
	v_mov_b64_e32 v[26:27], 0
	v_mov_b64_e32 v[28:29], 0
	v_mov_b64_e32 v[30:31], 0
	v_mov_b64_e32 v[0:1], 0
	v_mov_b64_e32 v[2:3], 0
	v_mov_b64_e32 v[4:5], 0
	v_mov_b64_e32 v[6:7], 0
	v_mov_b64_e32 v[8:9], 0
	v_mov_b64_e32 v[10:11], 0
	v_mov_b64_e32 v[12:13], 0
	v_mov_b64_e32 v[14:15], 0
	v_mov_b64_e32 v[48:49], 0
	v_mov_b64_e32 v[50:51], 0
	v_mov_b64_e32 v[52:53], 0
	v_mov_b64_e32 v[54:55], 0
	v_mov_b64_e32 v[56:57], 0
	v_mov_b64_e32 v[58:59], 0
	v_mov_b64_e32 v[60:61], 0
	v_mov_b64_e32 v[62:63], 0
	v_mov_b64_e32 v[32:33], 0
	v_mov_b64_e32 v[34:35], 0
	v_mov_b64_e32 v[36:37], 0
	v_mov_b64_e32 v[38:39], 0
	v_mov_b64_e32 v[40:41], 0
	v_mov_b64_e32 v[42:43], 0
	v_mov_b64_e32 v[44:45], 0
	v_mov_b64_e32 v[46:47], 0
	v_mov_b32_e32 v65, 0
	v_mov_b32_e32 v64, 0
	v_mov_b32_e32 v244, 0xf149f2ca
	v_mov_b32_e32 v245, 0xf149f2ca
	s_sub_i32 s94, 18, s92
	s_mov_b32 s29, 0
	s_mov_b32 s95, s92
	s_mov_b32 s96, s31
	v_add_u32_e32 v147, s31, v158
	v_readfirstlane_b32 s0, v168
	v_readfirstlane_b32 s1, v169
	v_readfirstlane_b32 s4, v170
	v_readfirstlane_b32 s5, v171
	s_add_i32 s6, s28, 2
	s_lshl_b32 s6, s6, 12
	s_add_u32 s0, s0, s6
	s_addc_u32 s1, s1, 0
	s_add_u32 s4, s4, s6
	s_addc_u32 s5, s5, 0
	v_add_lshl_u32 v149, v182, s93, 2
	s_lshl_b32 s6, s92, 7
	v_sub_u32_e32 v149, s6, v149
	v_add_u32_e32 v148, v184, v149
	v_add_u32_e32 v148, 0xffffff00, v148
	ds_read_b128 v[130:133], v147
	ds_read_b128 v[134:137], v147 offset:1024
	ds_read_b128 v[138:141], v147 offset:2048
	ds_read_b128 v[142:145], v147 offset:3072
	s_and_b64 vcc, exec, s[26:27]
	s_cbranch_vccz .Lat_a_top_q1
; #define LAS __attribute__((address_space(3)))
; #define MFMA32(a, b, c) __builtin_amdgcn_mfma_f32_32x32x16_bf16((a), (b), (c), 0, 0, 0)
; template <bool ISB>
; DI void attn_block(const LAS unsigned char* slot, const bf16x8 (&qf)[2][4], f32x16 (&o)[2][2], float (&mrun)[2], float (&lrun)[2], int kb, int r, int hh, int lane, const LAS float* biasR, float bconst, int qoff, int nq) {
;     ...
;     for (int qb = 0; qb < 2; ++qb) {
;         if (qb >= nq) continue;
;         f32x16 s;
; #pragma unroll
;         for (int i = 0; i < 16; ++i) s[i] = 0.f;
; #pragma unroll
;         for (int ds = 0; ds < 4; ++ds) s = MFMA32(kf[ds], qf[qb][ds], s);
;         float cadd = 0.f;
;         if (!ISB) {
;             if (kb >= 12) {
;                 const LAS float* bp = biasR + (191 - (512 + qoff + 32 * qb + r - 32 * kb - 4 * hh));
; #pragma unroll
;                 for (int i = 0; i < 16; ++i) s[i] += bp[8 * (i >> 2) + (i & 3)];
;             } else cadd = bconst;
;         }
;         float mx = fmaxf(fmaxf(s[0], s[1]), s[2]);
; #pragma unroll
;         for (int i = 3; i < 15; i += 2) mx = fmaxf(fmaxf(mx, s[i]), s[i + 1]);
;         mx = fmaxf(mx, s[15]);
;         mx = fmaxf(mx, __shfl_xor(mx, 32)) + cadd;
;         if (__any(mx > mrun[qb] + 8.f)) {
;             const float mnew = fmaxf(mrun[qb], mx), alpha = __builtin_amdgcn_exp2f(mrun[qb] - mnew);
;             mrun[qb] = mnew; lrun[qb] *= alpha;
; #pragma unroll
;             for (int i = 0; i < 16; ++i) { o[qb][0][i] *= alpha; o[qb][1][i] *= alpha; }
;         }
.Lat_a_top_q2:
	ds_read_b128 v[194:197], v147 offset:4096
	ds_read_b128 v[198:201], v147 offset:5120
	ds_read_b128 v[202:205], v147 offset:6144
	ds_read_b128 v[206:209], v147 offset:7168
	s_waitcnt lgkmcnt(4)
	s_cmp_lt_u32 s95, 12
	s_cbranch_scc1 .Lat_a_nobias_q2
	v_mfma_f32_32x32x16_bf16 v[66:81], v[130:133], v[98:101], 0
	ds_read2_b32 v[210:211], v148 offset0:32 offset1:33
	ds_read2_b32 v[212:213], v148 offset0:34 offset1:35
	ds_read2_b32 v[214:215], v148 offset0:40 offset1:41
	ds_read2_b32 v[216:217], v148 offset0:42 offset1:43
	ds_read2_b32 v[218:219], v148 offset0:48 offset1:49
	ds_read2_b32 v[220:221], v148 offset0:50 offset1:51
	ds_read2_b32 v[222:223], v148 offset0:56 offset1:57
	ds_read2_b32 v[224:225], v148 offset0:58 offset1:59
	v_mfma_f32_32x32x16_bf16 v[66:81], v[134:137], v[102:105], v[66:81]
	v_mfma_f32_32x32x16_bf16 v[66:81], v[138:141], v[106:109], v[66:81]
	v_mfma_f32_32x32x16_bf16 v[66:81], v[142:145], v[110:113], v[66:81]
	v_mfma_f32_32x32x16_bf16 v[82:97], v[130:133], v[114:117], 0
	ds_read2_b32 v[228:229], v148 offset0:0 offset1:1
	ds_read2_b32 v[230:231], v148 offset0:2 offset1:3
	ds_read2_b32 v[232:233], v148 offset0:8 offset1:9
	ds_read2_b32 v[234:235], v148 offset0:10 offset1:11
	ds_read2_b32 v[236:237], v148 offset0:16 offset1:17
	ds_read2_b32 v[238:239], v148 offset0:18 offset1:19
	ds_read2_b32 v[240:241], v148 offset0:24 offset1:25
	ds_read2_b32 v[242:243], v148 offset0:26 offset1:27
	v_mfma_f32_32x32x16_bf16 v[82:97], v[134:137], v[118:121], v[82:97]
	v_mfma_f32_32x32x16_bf16 v[82:97], v[138:141], v[122:125], v[82:97]
	v_mfma_f32_32x32x16_bf16 v[82:97], v[142:145], v[126:129], v[82:97]
	v_mov_b32_e32 v146, 0
	s_waitcnt lgkmcnt(8)
	v_add_f32_e32 v66, v66, v210
	v_add_f32_e32 v67, v67, v211
	v_add_f32_e32 v68, v68, v212
	v_add_f32_e32 v69, v69, v213
	v_add_f32_e32 v70, v70, v214
	v_add_f32_e32 v71, v71, v215
	v_add_f32_e32 v72, v72, v216
	v_add_f32_e32 v73, v73, v217
	v_add_f32_e32 v74, v74, v218
	v_add_f32_e32 v75, v75, v219
	v_add_f32_e32 v76, v76, v220
	v_add_f32_e32 v77, v77, v221
	v_add_f32_e32 v78, v78, v222
	v_add_f32_e32 v79, v79, v223
	v_add_f32_e32 v80, v80, v224
	v_add_f32_e32 v81, v81, v225
	s_waitcnt lgkmcnt(0)
	v_add_f32_e32 v82, v82, v228
	v_add_f32_e32 v83, v83, v229
	v_add_f32_e32 v84, v84, v230
	v_add_f32_e32 v85, v85, v231
	v_add_f32_e32 v86, v86, v232
	v_add_f32_e32 v87, v87, v233
	v_add_f32_e32 v88, v88, v234
	v_add_f32_e32 v89, v89, v235
	v_add_f32_e32 v90, v90, v236
	v_add_f32_e32 v91, v91, v237
	v_add_f32_e32 v92, v92, v238
	v_add_f32_e32 v93, v93, v239
	v_add_f32_e32 v94, v94, v240
	v_add_f32_e32 v95, v95, v241
	v_add_f32_e32 v96, v96, v242
	v_add_f32_e32 v97, v97, v243
	s_branch .Lat_a_smax_q2
.Lat_a_nobias_q2:
	v_mfma_f32_32x32x16_bf16 v[66:81], v[130:133], v[98:101], 0
	v_mfma_f32_32x32x16_bf16 v[66:81], v[134:137], v[102:105], v[66:81]
	v_mfma_f32_32x32x16_bf16 v[66:81], v[138:141], v[106:109], v[66:81]
	v_mfma_f32_32x32x16_bf16 v[66:81], v[142:145], v[110:113], v[66:81]
	v_mfma_f32_32x32x16_bf16 v[82:97], v[130:133], v[114:117], 0
	v_mfma_f32_32x32x16_bf16 v[82:97], v[134:137], v[118:121], v[82:97]
	v_mfma_f32_32x32x16_bf16 v[82:97], v[138:141], v[122:125], v[82:97]
	v_mfma_f32_32x32x16_bf16 v[82:97], v[142:145], v[126:129], v[82:97]
	v_mov_b32_e32 v146, v189
	s_nop 6
.Lat_a_smax_q2:
	v_max3_f32 v246, v66, v67, v68
	v_max3_f32 v246, v246, v69, v70
	v_max3_f32 v246, v246, v71, v72
	v_max3_f32 v246, v246, v73, v74
	v_max3_f32 v246, v246, v75, v76
	v_max3_f32 v246, v246, v77, v78
	v_max3_f32 v246, v246, v79, v80
	v_max_f32_e32 v246, v246, v81
	v_max3_f32 v247, v82, v83, v84
	v_max3_f32 v247, v247, v85, v86
	v_max3_f32 v247, v247, v87, v88
	v_max3_f32 v247, v247, v89, v90
	v_max3_f32 v247, v247, v91, v92
	v_max3_f32 v247, v247, v93, v94
	v_max3_f32 v247, v247, v95, v96
	v_max_f32_e32 v247, v247, v97
	v_mov_b32_e32 v248, v246
	v_mov_b32_e32 v249, v247
	s_nop 0
	v_permlane32_swap_b32_e32 v248, v246
	v_permlane32_swap_b32_e32 v249, v247
	v_max_f32_e32 v246, v246, v248
	v_max_f32_e32 v247, v247, v249
	v_add_f32_e32 v153, v246, v146
	v_add_f32_e32 v248, v244, v177
	v_add_f32_e32 v154, v247, v146
	v_add_f32_e32 v249, v245, v177
	v_cmp_gt_f32_e32 vcc, v153, v248
	s_cbranch_vccz .Lat_a_nors0_q2
	v_max_f32_e32 v248, v244, v153
	v_sub_f32_e32 v151, v244, v248
	v_exp_f32_e32 v151, v151
	v_mov_b32_e32 v244, v248
	s_nop 0
	v_mul_f32_e32 v65, v65, v151
	v_mul_f32_e32 v16, v16, v151
	v_mul_f32_e32 v17, v17, v151
	v_mul_f32_e32 v18, v18, v151
	v_mul_f32_e32 v19, v19, v151
	v_mul_f32_e32 v20, v20, v151
	v_mul_f32_e32 v21, v21, v151
	v_mul_f32_e32 v22, v22, v151
	v_mul_f32_e32 v23, v23, v151
	v_mul_f32_e32 v24, v24, v151
	v_mul_f32_e32 v25, v25, v151
	v_mul_f32_e32 v26, v26, v151
	v_mul_f32_e32 v27, v27, v151
	v_mul_f32_e32 v28, v28, v151
	v_mul_f32_e32 v29, v29, v151
	v_mul_f32_e32 v30, v30, v151
	v_mul_f32_e32 v31, v31, v151
	v_mul_f32_e32 v0, v0, v151
	v_mul_f32_e32 v1, v1, v151
	v_mul_f32_e32 v2, v2, v151
	v_mul_f32_e32 v3, v3, v151
	v_mul_f32_e32 v4, v4, v151
	v_mul_f32_e32 v5, v5, v151
	v_mul_f32_e32 v6, v6, v151
	v_mul_f32_e32 v7, v7, v151
	v_mul_f32_e32 v8, v8, v151
	v_mul_f32_e32 v9, v9, v151
	v_mul_f32_e32 v10, v10, v151
	v_mul_f32_e32 v11, v11, v151
	v_mul_f32_e32 v12, v12, v151
	v_mul_f32_e32 v13, v13, v151
	v_mul_f32_e32 v14, v14, v151
	v_mul_f32_e32 v15, v15, v151
; #define MFMA32(a, b, c) __builtin_amdgcn_mfma_f32_32x32x16_bf16((a), (b), (c), 0, 0, 0)
; template <bool ISB>
; DI void attn_block(const LAS unsigned char* slot, const bf16x8 (&qf)[2][4], f32x16 (&o)[2][2], float (&mrun)[2], float (&lrun)[2], int kb, int r, int hh, int lane, const LAS float* biasR, float bconst, int qoff, int nq) {
;     ...
;         if (__any(mx > mrun[qb] + 8.f)) {
;             const float mnew = fmaxf(mrun[qb], mx), alpha = __builtin_amdgcn_exp2f(mrun[qb] - mnew);
;             mrun[qb] = mnew; lrun[qb] *= alpha;
; #pragma unroll
;             for (int i = 0; i < 16; ++i) { o[qb][0][i] *= alpha; o[qb][1][i] *= alpha; }
;         }
;         const float c = cadd - mrun[qb];
;         float psum = 0.f;
; #pragma unroll
;         for (int i = 0; i < 16; ++i) { s[i] = __builtin_amdgcn_exp2f(s[i] + c); psum += s[i]; }
;         lrun[qb] += psum;
;         bf16x8 pf[2];
; #pragma unroll
;         for (int t = 0; t < 2; ++t) { u32x4 p; p.x = pk2(s[8 * t], s[8 * t + 1]); p.y = pk2(s[8 * t + 2], s[8 * t + 3]); p.z = pk2(s[8 * t + 4], s[8 * t + 5]); p.w = pk2(s[8 * t + 6], s[8 * t + 7]);
;             pf[t] = __builtin_bit_cast(bf16x8, p); }
; #pragma unroll
;         for (int db = 0; db < 2; ++db)
; #pragma unroll
;             for (int t = 0; t < 2; ++t) o[qb][db] = MFMA32(vf[db][t], pf[t], o[qb][db]);
; template <bool ISB>
; DI void attn_unit(int u, int hq, int qoff, int nq, const bf16_t* Qb, const bf16_t* Kb, const bf16_t* Vtb, bf16_t* O, const float* sinks, const LAS float* biasL, LAS unsigned char* ring, int lane) {
;     ...
;         if (ib + 2 < nb) { asm volatile("s_waitcnt lgkmcnt(0)" ::: "memory"); __builtin_amdgcn_sched_barrier(0); kv_dma(Kp, Vp, blk0 + ib + 2, slot); }
.Lat_a_nors0_q2:
	v_cmp_gt_f32_e32 vcc, v154, v249
	s_cbranch_vccz .Lat_a_nors1_q2
	v_max_f32_e32 v249, v245, v154
	v_sub_f32_e32 v152, v245, v249
	v_exp_f32_e32 v152, v152
	v_mov_b32_e32 v245, v249
	s_nop 0
	v_mul_f32_e32 v64, v64, v152
	v_mul_f32_e32 v48, v48, v152
	v_mul_f32_e32 v49, v49, v152
	v_mul_f32_e32 v50, v50, v152
	v_mul_f32_e32 v51, v51, v152
	v_mul_f32_e32 v52, v52, v152
	v_mul_f32_e32 v53, v53, v152
	v_mul_f32_e32 v54, v54, v152
	v_mul_f32_e32 v55, v55, v152
	v_mul_f32_e32 v56, v56, v152
	v_mul_f32_e32 v57, v57, v152
	v_mul_f32_e32 v58, v58, v152
	v_mul_f32_e32 v59, v59, v152
	v_mul_f32_e32 v60, v60, v152
	v_mul_f32_e32 v61, v61, v152
	v_mul_f32_e32 v62, v62, v152
	v_mul_f32_e32 v63, v63, v152
	v_mul_f32_e32 v32, v32, v152
	v_mul_f32_e32 v33, v33, v152
	v_mul_f32_e32 v34, v34, v152
	v_mul_f32_e32 v35, v35, v152
	v_mul_f32_e32 v36, v36, v152
	v_mul_f32_e32 v37, v37, v152
	v_mul_f32_e32 v38, v38, v152
	v_mul_f32_e32 v39, v39, v152
	v_mul_f32_e32 v40, v40, v152
	v_mul_f32_e32 v41, v41, v152
	v_mul_f32_e32 v42, v42, v152
	v_mul_f32_e32 v43, v43, v152
	v_mul_f32_e32 v44, v44, v152
	v_mul_f32_e32 v45, v45, v152
	v_mul_f32_e32 v46, v46, v152
	v_mul_f32_e32 v47, v47, v152
.Lat_a_nors1_q2:
	v_sub_f32_e32 v250, v146, v244
	v_sub_f32_e32 v251, v146, v245
	v_add_f32_e32 v66, v66, v250
	v_exp_f32_e32 v210, v66
	v_add_f32_e32 v67, v67, v250
	v_exp_f32_e32 v211, v67
	v_add_f32_e32 v68, v68, v250
	v_exp_f32_e32 v212, v68
	v_add_f32_e32 v69, v69, v250
	v_exp_f32_e32 v213, v69
	v_add_f32_e32 v70, v70, v250
	v_exp_f32_e32 v214, v70
	v_add_f32_e32 v71, v71, v250
	v_exp_f32_e32 v215, v71
	v_add_f32_e32 v72, v72, v250
	v_exp_f32_e32 v216, v72
	v_add_f32_e32 v73, v73, v250
	v_exp_f32_e32 v217, v73
	v_add_f32_e32 v74, v74, v250
	v_exp_f32_e32 v218, v74
	v_add_f32_e32 v75, v75, v250
	v_exp_f32_e32 v219, v75
	v_add_f32_e32 v76, v76, v250
	v_exp_f32_e32 v220, v76
	v_add_f32_e32 v77, v77, v250
	v_exp_f32_e32 v221, v77
	v_add_f32_e32 v78, v78, v250
	v_exp_f32_e32 v222, v78
	v_add_f32_e32 v79, v79, v250
	v_exp_f32_e32 v223, v79
	v_add_f32_e32 v80, v80, v250
	v_exp_f32_e32 v224, v80
	v_add_f32_e32 v81, v81, v250
	v_exp_f32_e32 v225, v81
	v_cvt_pk_bf16_f32 v66, v210, v211
	v_cvt_pk_bf16_f32 v67, v212, v213
	v_cvt_pk_bf16_f32 v68, v214, v215
	v_cvt_pk_bf16_f32 v69, v216, v217
	v_cvt_pk_bf16_f32 v70, v218, v219
	v_cvt_pk_bf16_f32 v71, v220, v221
	v_cvt_pk_bf16_f32 v72, v222, v223
	v_cvt_pk_bf16_f32 v73, v224, v225
	s_waitcnt lgkmcnt(0)
	s_nop 0
	v_mfma_f32_32x32x16_bf16 v[16:31], v[194:197], v[66:69], v[16:31]
	v_add_f32_e32 v82, v82, v251
	v_exp_f32_e32 v228, v82
	v_add_f32_e32 v83, v83, v251
	v_exp_f32_e32 v229, v83
	v_add_f32_e32 v84, v84, v251
	v_exp_f32_e32 v230, v84
	v_add_f32_e32 v85, v85, v251
	v_exp_f32_e32 v231, v85
	v_mfma_f32_32x32x16_bf16 v[0:15], v[202:205], v[66:69], v[0:15]
	v_add_f32_e32 v86, v86, v251
	v_exp_f32_e32 v232, v86
	v_add_f32_e32 v87, v87, v251
	v_exp_f32_e32 v233, v87
	v_add_f32_e32 v88, v88, v251
	v_exp_f32_e32 v234, v88
	v_add_f32_e32 v89, v89, v251
	v_exp_f32_e32 v235, v89
	v_mfma_f32_32x32x16_bf16 v[16:31], v[198:201], v[70:73], v[16:31]
	v_add_f32_e32 v90, v90, v251
	v_exp_f32_e32 v236, v90
	v_add_f32_e32 v91, v91, v251
	v_exp_f32_e32 v237, v91
	v_add_f32_e32 v92, v92, v251
	v_exp_f32_e32 v238, v92
	v_add_f32_e32 v93, v93, v251
	v_exp_f32_e32 v239, v93
	v_mfma_f32_32x32x16_bf16 v[0:15], v[206:209], v[70:73], v[0:15]
	v_add_f32_e32 v94, v94, v251
	v_exp_f32_e32 v240, v94
	v_add_f32_e32 v95, v95, v251
	v_exp_f32_e32 v241, v95
	v_add_f32_e32 v96, v96, v251
	v_exp_f32_e32 v242, v96
	v_add_f32_e32 v97, v97, v251
	v_exp_f32_e32 v243, v97
	v_cvt_pk_bf16_f32 v82, v228, v229
	v_cvt_pk_bf16_f32 v83, v230, v231
	v_cvt_pk_bf16_f32 v84, v232, v233
	v_cvt_pk_bf16_f32 v85, v234, v235
	v_cvt_pk_bf16_f32 v86, v236, v237
	v_cvt_pk_bf16_f32 v87, v238, v239
	v_cvt_pk_bf16_f32 v88, v240, v241
	v_cvt_pk_bf16_f32 v89, v242, v243
	s_nop 1
	v_mfma_f32_32x32x16_bf16 v[48:63], v[194:197], v[82:85], v[48:63]
	v_mov_b32_e32 v151, 0
	v_mov_b32_e32 v152, 0
	v_add_f32_e32 v151, v151, v210
	v_add_f32_e32 v152, v152, v228
	v_add_f32_e32 v151, v151, v211
	v_add_f32_e32 v152, v152, v229
	v_add_f32_e32 v151, v151, v212
	v_add_f32_e32 v152, v152, v230
	v_add_f32_e32 v151, v151, v213
	v_mfma_f32_32x32x16_bf16 v[32:47], v[202:205], v[82:85], v[32:47]
	v_add_f32_e32 v152, v152, v231
	v_add_f32_e32 v151, v151, v214
	v_add_f32_e32 v152, v152, v232
	v_add_f32_e32 v151, v151, v215
	v_add_f32_e32 v152, v152, v233
	v_add_f32_e32 v151, v151, v216
	v_add_f32_e32 v152, v152, v234
	v_add_f32_e32 v151, v151, v217
	v_add_f32_e32 v152, v152, v235
	v_mfma_f32_32x32x16_bf16 v[48:63], v[198:201], v[86:89], v[48:63]
	v_add_f32_e32 v151, v151, v218
	v_add_f32_e32 v152, v152, v236
	v_add_f32_e32 v151, v151, v219
	v_add_f32_e32 v152, v152, v237
	v_add_f32_e32 v151, v151, v220
	v_add_f32_e32 v152, v152, v238
	v_add_f32_e32 v151, v151, v221
	v_add_f32_e32 v152, v152, v239
	v_add_f32_e32 v151, v151, v222
	v_mfma_f32_32x32x16_bf16 v[32:47], v[206:209], v[86:89], v[32:47]
	v_add_f32_e32 v152, v152, v240
	v_add_f32_e32 v151, v151, v223
	v_add_f32_e32 v152, v152, v241
	v_add_f32_e32 v151, v151, v224
	v_add_f32_e32 v152, v152, v242
	v_add_f32_e32 v151, v151, v225
	v_add_f32_e32 v152, v152, v243
	v_add_f32_e32 v65, v65, v151
	v_add_f32_e32 v64, v64, v152
	s_add_i32 s29, s29, 1
	s_add_i32 s6, s29, 1
	s_cmp_ge_u32 s6, s94
	s_cbranch_scc1 .Lat_a_nodma_q2
	s_mov_b32 m0, s96
	s_nop 0
	global_load_lds_dwordx4 v158, s[0:1]
	global_load_lds_dwordx4 v158, s[0:1] offset:1024
	global_load_lds_dwordx4 v158, s[0:1] offset:2048
	global_load_lds_dwordx4 v158, s[0:1] offset:3072
	s_add_i32 m0, s96, 0x1000
	s_add_u32 s0, s0, 0x1000
	s_addc_u32 s1, s1, 0
	global_load_lds_dwordx4 v158, s[4:5]
	global_load_lds_dwordx4 v158, s[4:5] offset:1024
	global_load_lds_dwordx4 v158, s[4:5] offset:2048
	global_load_lds_dwordx4 v158, s[4:5] offset:3072
	s_add_u32 s4, s4, 0x1000
	s_addc_u32 s5, s5, 0
	s_waitcnt vmcnt(8)
	s_branch .Lat_a_kpre_q2

; template <bool ISB>
; DI void attn_block(const LAS unsigned char* slot, const bf16x8 (&qf)[2][4], f32x16 (&o)[2][2], float (&mrun)[2], float (&lrun)[2], int kb, int r, int hh, int lane, const LAS float* biasR, float bconst, int qoff, int nq) {
;     ...
;     for (int qb = 0; qb < 2; ++qb) {
;         if (qb >= nq) continue;
;         f32x16 s;
; #pragma unroll
;         for (int i = 0; i < 16; ++i) s[i] = 0.f;
; #pragma unroll
;         for (int ds = 0; ds < 4; ++ds) s = MFMA32(kf[ds], qf[qb][ds], s);
;         float cadd = 0.f;
;         if (!ISB) {
;             if (kb >= 12) {
;                 const LAS float* bp = biasR + (191 - (512 + qoff + 32 * qb + r - 32 * kb - 4 * hh));
; #pragma unroll
;                 for (int i = 0; i < 16; ++i) s[i] += bp[8 * (i >> 2) + (i & 3)];
;             } else cadd = bconst;
;         }
;         float mx = fmaxf(fmaxf(s[0], s[1]), s[2]);
; #pragma unroll
;         for (int i = 3; i < 15; i += 2) mx = fmaxf(fmaxf(mx, s[i]), s[i + 1]);
;         mx = fmaxf(mx, s[15]);
;         mx = fmaxf(mx, __shfl_xor(mx, 32)) + cadd;
;         if (__any(mx > mrun[qb] + 8.f)) {
;             const float mnew = fmaxf(mrun[qb], mx), alpha = __builtin_amdgcn_exp2f(mrun[qb] - mnew);
;             mrun[qb] = mnew; lrun[qb] *= alpha;
; #pragma unroll
;             for (int i = 0; i < 16; ++i) { o[qb][0][i] *= alpha; o[qb][1][i] *= alpha; }
;         }
;         const float c = cadd - mrun[qb];
;         float psum = 0.f;
; #pragma unroll
;         for (int i = 0; i < 16; ++i) { s[i] = __builtin_amdgcn_exp2f(s[i] + c); psum += s[i]; }
;         lrun[qb] += psum;
;         bf16x8 pf[2];
; #pragma unroll
;         for (int t = 0; t < 2; ++t) { u32x4 p; p.x = pk2(s[8 * t], s[8 * t + 1]); p.y = pk2(s[8 * t + 2], s[8 * t + 3]); p.z = pk2(s[8 * t + 4], s[8 * t + 5]); p.w = pk2(s[8 * t + 6], s[8 * t + 7]);
;             pf[t] = __builtin_bit_cast(bf16x8, p); }
; #pragma unroll
;         for (int db = 0; db < 2; ++db)
; #pragma unroll
;             for (int t = 0; t < 2; ++t) o[qb][db] = MFMA32(vf[db][t], pf[t], o[qb][db]);
; template <bool ISB>
; DI void attn_unit(int u, int hq, int qoff, int nq, const bf16_t* Qb, const bf16_t* Kb, const bf16_t* Vtb, bf16_t* O, const float* sinks, const LAS float* biasL, LAS unsigned char* ring, int lane) {
;     ...
;     for (int ib = 0; ib < nb; ++ib) {
;         LAS unsigned char* slot = ring + (ib & 1) * 8192;
.Lat_a_kpre_q2:
	s_xor_b32 s96, s96, 0x2000
	v_xor_b32_e32 v147, 0x2000, v147
	s_add_i32 s95, s95, 1
	v_add_u32_e32 v148, 0x80, v148
	ds_read_b128 v[130:133], v147
	ds_read_b128 v[134:137], v147 offset:1024
	ds_read_b128 v[138:141], v147 offset:2048
	ds_read_b128 v[142:145], v147 offset:3072
	s_branch .Lat_a_top_q2
.Lat_a_top_q1:
	ds_read_b128 v[194:197], v147 offset:4096
	ds_read_b128 v[198:201], v147 offset:5120
	ds_read_b128 v[202:205], v147 offset:6144
	ds_read_b128 v[206:209], v147 offset:7168
	s_waitcnt lgkmcnt(4)
	s_cmp_lt_u32 s95, 12
	s_cbranch_scc1 .Lat_a_nobias_q1
	v_mfma_f32_32x32x16_bf16 v[66:81], v[130:133], v[98:101], 0
	ds_read2_b32 v[210:211], v148 offset0:32 offset1:33
	ds_read2_b32 v[212:213], v148 offset0:34 offset1:35
	ds_read2_b32 v[214:215], v148 offset0:40 offset1:41
	ds_read2_b32 v[216:217], v148 offset0:42 offset1:43
	ds_read2_b32 v[218:219], v148 offset0:48 offset1:49
	ds_read2_b32 v[220:221], v148 offset0:50 offset1:51
	ds_read2_b32 v[222:223], v148 offset0:56 offset1:57
	ds_read2_b32 v[224:225], v148 offset0:58 offset1:59
	v_mfma_f32_32x32x16_bf16 v[66:81], v[134:137], v[102:105], v[66:81]
	v_mfma_f32_32x32x16_bf16 v[66:81], v[138:141], v[106:109], v[66:81]
	v_mfma_f32_32x32x16_bf16 v[66:81], v[142:145], v[110:113], v[66:81]
	v_mov_b32_e32 v146, 0
	s_waitcnt lgkmcnt(0)
	s_nop 9
	v_add_f32_e32 v66, v66, v210
	v_add_f32_e32 v67, v67, v211
	v_add_f32_e32 v68, v68, v212
	v_add_f32_e32 v69, v69, v213
	v_add_f32_e32 v70, v70, v214
	v_add_f32_e32 v71, v71, v215
	v_add_f32_e32 v72, v72, v216
	v_add_f32_e32 v73, v73, v217
	v_add_f32_e32 v74, v74, v218
	v_add_f32_e32 v75, v75, v219
	v_add_f32_e32 v76, v76, v220
	v_add_f32_e32 v77, v77, v221
	v_add_f32_e32 v78, v78, v222
	v_add_f32_e32 v79, v79, v223
	v_add_f32_e32 v80, v80, v224
	v_add_f32_e32 v81, v81, v225
	s_branch .Lat_a_smax_q1
.Lat_a_nobias_q1:
	v_mfma_f32_32x32x16_bf16 v[66:81], v[130:133], v[98:101], 0
	v_mfma_f32_32x32x16_bf16 v[66:81], v[134:137], v[102:105], v[66:81]
	v_mfma_f32_32x32x16_bf16 v[66:81], v[138:141], v[106:109], v[66:81]
	v_mfma_f32_32x32x16_bf16 v[66:81], v[142:145], v[110:113], v[66:81]
	v_mov_b32_e32 v146, v189
	s_nop 10
.Lat_a_smax_q1:
	v_max3_f32 v246, v66, v67, v68
	v_max3_f32 v246, v246, v69, v70
	v_max3_f32 v246, v246, v71, v72
	v_max3_f32 v246, v246, v73, v74
	v_max3_f32 v246, v246, v75, v76
	v_max3_f32 v246, v246, v77, v78
	v_max3_f32 v246, v246, v79, v80
	v_max_f32_e32 v246, v246, v81
	v_mov_b32_e32 v248, v246
	s_nop 1
	v_permlane32_swap_b32_e32 v248, v246
	v_max_f32_e32 v246, v246, v248
	v_add_f32_e32 v153, v246, v146
	v_add_f32_e32 v248, v244, v177
	v_cmp_gt_f32_e32 vcc, v153, v248
	s_cbranch_vccz .Lat_a_nors0_q1
	v_max_f32_e32 v248, v244, v153
	v_sub_f32_e32 v151, v244, v248
	v_exp_f32_e32 v151, v151
	v_mov_b32_e32 v244, v248
	s_nop 0
	v_mul_f32_e32 v65, v65, v151
	v_mul_f32_e32 v16, v16, v151
	v_mul_f32_e32 v17, v17, v151
	v_mul_f32_e32 v18, v18, v151
	v_mul_f32_e32 v19, v19, v151
	v_mul_f32_e32 v20, v20, v151
	v_mul_f32_e32 v21, v21, v151
	v_mul_f32_e32 v22, v22, v151
	v_mul_f32_e32 v23, v23, v151
	v_mul_f32_e32 v24, v24, v151
	v_mul_f32_e32 v25, v25, v151
	v_mul_f32_e32 v26, v26, v151
	v_mul_f32_e32 v27, v27, v151
	v_mul_f32_e32 v28, v28, v151
	v_mul_f32_e32 v29, v29, v151
	v_mul_f32_e32 v30, v30, v151
	v_mul_f32_e32 v31, v31, v151
	v_mul_f32_e32 v0, v0, v151
	v_mul_f32_e32 v1, v1, v151
	v_mul_f32_e32 v2, v2, v151
	v_mul_f32_e32 v3, v3, v151
	v_mul_f32_e32 v4, v4, v151
	v_mul_f32_e32 v5, v5, v151
	v_mul_f32_e32 v6, v6, v151
	v_mul_f32_e32 v7, v7, v151
	v_mul_f32_e32 v8, v8, v151
	v_mul_f32_e32 v9, v9, v151
	v_mul_f32_e32 v10, v10, v151
	v_mul_f32_e32 v11, v11, v151
	v_mul_f32_e32 v12, v12, v151
	v_mul_f32_e32 v13, v13, v151
	v_mul_f32_e32 v14, v14, v151
	v_mul_f32_e32 v15, v15, v151
.Lat_a_nors0_q1:
	v_sub_f32_e32 v250, v146, v244
	v_add_f32_e32 v66, v66, v250
	v_exp_f32_e32 v210, v66
	v_add_f32_e32 v67, v67, v250
	v_exp_f32_e32 v211, v67
	v_add_f32_e32 v68, v68, v250
	v_exp_f32_e32 v212, v68
	v_add_f32_e32 v69, v69, v250
	v_exp_f32_e32 v213, v69
	v_add_f32_e32 v70, v70, v250
	v_exp_f32_e32 v214, v70
	v_add_f32_e32 v71, v71, v250
	v_exp_f32_e32 v215, v71
	v_add_f32_e32 v72, v72, v250
	v_exp_f32_e32 v216, v72
	v_add_f32_e32 v73, v73, v250
	v_exp_f32_e32 v217, v73
	v_add_f32_e32 v74, v74, v250
	v_exp_f32_e32 v218, v74
	v_add_f32_e32 v75, v75, v250
	v_exp_f32_e32 v219, v75
	v_add_f32_e32 v76, v76, v250
	v_exp_f32_e32 v220, v76
	v_add_f32_e32 v77, v77, v250
	v_exp_f32_e32 v221, v77
	v_add_f32_e32 v78, v78, v250
	v_exp_f32_e32 v222, v78
	v_add_f32_e32 v79, v79, v250
	v_exp_f32_e32 v223, v79
	v_add_f32_e32 v80, v80, v250
	v_exp_f32_e32 v224, v80
	v_add_f32_e32 v81, v81, v250
	v_exp_f32_e32 v225, v81
	v_cvt_pk_bf16_f32 v66, v210, v211
	v_cvt_pk_bf16_f32 v67, v212, v213
	v_cvt_pk_bf16_f32 v68, v214, v215
	v_cvt_pk_bf16_f32 v69, v216, v217
	v_cvt_pk_bf16_f32 v70, v218, v219
	v_cvt_pk_bf16_f32 v71, v220, v221
	v_cvt_pk_bf16_f32 v72, v222, v223
	v_cvt_pk_bf16_f32 v73, v224, v225
	s_waitcnt lgkmcnt(0)
	s_nop 0
	v_mfma_f32_32x32x16_bf16 v[16:31], v[194:197], v[66:69], v[16:31]
	v_mov_b32_e32 v151, 0
	v_add_f32_e32 v151, v151, v210
	v_add_f32_e32 v151, v151, v211
	v_add_f32_e32 v151, v151, v212
	v_add_f32_e32 v151, v151, v213
	v_mfma_f32_32x32x16_bf16 v[0:15], v[202:205], v[66:69], v[0:15]
	v_add_f32_e32 v151, v151, v214
	v_add_f32_e32 v151, v151, v215
	v_add_f32_e32 v151, v151, v216
	v_add_f32_e32 v151, v151, v217
	v_add_f32_e32 v151, v151, v218
	v_mfma_f32_32x32x16_bf16 v[16:31], v[198:201], v[70:73], v[16:31]
	v_add_f32_e32 v151, v151, v219
	v_add_f32_e32 v151, v151, v220
	v_add_f32_e32 v151, v151, v221
	v_add_f32_e32 v151, v151, v222
	v_mfma_f32_32x32x16_bf16 v[0:15], v[206:209], v[70:73], v[0:15]
	v_add_f32_e32 v151, v151, v223
	v_add_f32_e32 v151, v151, v224
	v_add_f32_e32 v151, v151, v225
	v_add_f32_e32 v65, v65, v151
	s_add_i32 s29, s29, 1
	s_add_i32 s6, s29, 1
	s_cmp_ge_u32 s6, s94
	s_cbranch_scc1 .Lat_a_nodma_q1
	s_mov_b32 m0, s96
	s_nop 0
	global_load_lds_dwordx4 v158, s[0:1]
	global_load_lds_dwordx4 v158, s[0:1] offset:1024
	global_load_lds_dwordx4 v158, s[0:1] offset:2048
	global_load_lds_dwordx4 v158, s[0:1] offset:3072
	s_add_i32 m0, s96, 0x1000
	s_add_u32 s0, s0, 0x1000
	s_addc_u32 s1, s1, 0
	global_load_lds_dwordx4 v158, s[4:5]
	global_load_lds_dwordx4 v158, s[4:5] offset:1024
	global_load_lds_dwordx4 v158, s[4:5] offset:2048
	global_load_lds_dwordx4 v158, s[4:5] offset:3072
	s_add_u32 s4, s4, 0x1000
	s_addc_u32 s5, s5, 0
	s_waitcnt vmcnt(8)
	s_branch .Lat_a_kpre_q1

; DI u32x2 pk4(f32x4 v) { u32x2 r; r.x = pk2(v[0], v[1]); r.y = pk2(v[2], v[3]); return r; }
; template <bool ISB>
; DI void attn_unit(int u, int hq, int qoff, int nq, const bf16_t* Qb, const bf16_t* Kb, const bf16_t* Vtb, bf16_t* O, const float* sinks, const LAS float* biasL, LAS unsigned char* ring, int lane) {
;     ...
; #pragma unroll
;     for (int qb = 0; qb < 2; ++qb) {
;         if (qb >= nq) continue;
;         const float l = lrun[qb] + __shfl_xor(lrun[qb], 32), inv = 1.f / l;
;         bf16_t* op = O + (size_t)(64 * u + qoff + 32 * qb + r) * DM + (ISB ? 512 : 0) + hq * 64 + 4 * hh;
; #pragma unroll
;         for (int db = 0; db < 2; ++db)
; #pragma unroll
;             for (int i4 = 0; i4 < 4; ++i4) { f32x4 v = {o[qb][db][4 * i4] * inv, o[qb][db][4 * i4 + 1] * inv, o[qb][db][4 * i4 + 2] * inv, o[qb][db][4 * i4 + 3] * inv};
;                 *(u32x2*)(op + 32 * db + 8 * i4) = pk4(v); }
;     }
.Lat_a_done:
	v_mbcnt_hi_u32_b32 v191, -1, v185
	v_and_b32_e32 v193, 64, v191
	v_xor_b32_e32 v192, 32, v191
	v_add_u32_e32 v193, 64, v193
	s_branch .LBB0_696
.LBB0_652:
	v_mov_b32_e32 v16, v161
	v_mov_b32_e32 v17, v161
	v_mov_b32_e32 v30, v161
	v_mov_b32_e32 v31, v161
	v_mov_b32_e32 v18, v161
	v_mov_b32_e32 v19, v161
	v_mov_b32_e32 v20, v161
	v_mov_b32_e32 v21, v161
	v_mov_b32_e32 v22, v161
	v_mov_b32_e32 v23, v161
	v_mov_b32_e32 v24, v161
	v_mov_b32_e32 v25, v161
	v_mov_b32_e32 v26, v161
	v_mov_b32_e32 v27, v161
	v_mov_b32_e32 v28, v161
	v_mov_b32_e32 v29, v161
	v_mov_b64_e32 v[0:1], v[16:17]
	v_mov_b64_e32 v[62:63], v[30:31]
	v_mov_b64_e32 v[46:47], v[30:31]
	v_mov_b32_e32 v65, 0
	v_mov_b32_e32 v64, 0
	v_mov_b64_e32 v[2:3], v[18:19]
	v_mov_b64_e32 v[4:5], v[20:21]
	v_mov_b64_e32 v[6:7], v[22:23]
	v_mov_b64_e32 v[8:9], v[24:25]
	v_mov_b64_e32 v[10:11], v[26:27]
	v_mov_b64_e32 v[12:13], v[28:29]
	v_mov_b64_e32 v[14:15], v[30:31]
	v_mov_b64_e32 v[60:61], v[28:29]
	v_mov_b64_e32 v[58:59], v[26:27]
	v_mov_b64_e32 v[56:57], v[24:25]
	v_mov_b64_e32 v[54:55], v[22:23]
	v_mov_b64_e32 v[52:53], v[20:21]
	v_mov_b64_e32 v[50:51], v[18:19]
	v_mov_b64_e32 v[48:49], v[16:17]
	v_mov_b64_e32 v[44:45], v[28:29]
	v_mov_b64_e32 v[42:43], v[26:27]
	v_mov_b64_e32 v[40:41], v[24:25]
	v_mov_b64_e32 v[38:39], v[22:23]
	v_mov_b64_e32 v[36:37], v[20:21]
	v_mov_b64_e32 v[34:35], v[18:19]
	v_mov_b64_e32 v[32:33], v[16:17]
	s_branch .LBB0_696
.LBB0_696:
	v_cmp_lt_i32_e32 vcc, v192, v193
	s_nop 1
	v_cndmask_b32_e32 v66, v191, v192, vcc
	v_lshlrev_b32_e32 v68, 2, v66
	ds_bpermute_b32 v67, v68, v65
	v_or_b32_e32 v66, s91, v188
	s_waitcnt lgkmcnt(0)
	v_add_f32_e32 v65, v65, v67
	v_div_scale_f32 v69, s[0:1], v65, v65, 1.0
	v_rcp_f32_e32 v70, v69
	v_div_scale_f32 v71, vcc, 1.0, v65, 1.0
	v_ashrrev_i32_e32 v67, 31, v66
	v_fma_f32 v72, -v69, v70, 1.0
	v_fmac_f32_e32 v70, v72, v70
	v_mul_f32_e32 v72, v71, v70
	v_fma_f32 v73, -v69, v72, v71
	v_fmac_f32_e32 v72, v73, v70
	v_fma_f32 v69, -v69, v72, v71
	v_div_fmas_f32 v69, v69, v70, v72
	v_div_fixup_f32 v70, v69, v65, 1.0
	v_lshlrev_b64 v[72:73], 11, v[66:67]
	v_pk_mul_f32 v[16:17], v[16:17], v[70:71] op_sel_hi:[1,0]
	v_pk_mul_f32 v[18:19], v[18:19], v[70:71] op_sel_hi:[1,0]
	v_pk_mul_f32 v[0:1], v[0:1], v[70:71] op_sel_hi:[1,0]
	v_pk_mul_f32 v[2:3], v[2:3], v[70:71] op_sel_hi:[1,0]
	v_lshl_add_u64 v[72:73], v[174:175], 0, v[72:73]
	v_cvt_pk_bf16_f32 v16, v16, v17
	v_cvt_pk_bf16_f32 v17, v18, v19
	v_cvt_pk_bf16_f32 v0, v0, v1
	v_cvt_pk_bf16_f32 v1, v2, v3
	global_store_dwordx2 v[72:73], v[16:17], off
	v_pk_mul_f32 v[16:17], v[20:21], v[70:71] op_sel_hi:[1,0]
	v_pk_mul_f32 v[18:19], v[22:23], v[70:71] op_sel_hi:[1,0]
	global_store_dwordx2 v[72:73], v[0:1], off offset:64
	v_pk_mul_f32 v[0:1], v[4:5], v[70:71] op_sel_hi:[1,0]
	v_pk_mul_f32 v[2:3], v[6:7], v[70:71] op_sel_hi:[1,0]
	v_cvt_pk_bf16_f32 v16, v16, v17
	v_cvt_pk_bf16_f32 v17, v18, v19
	v_cvt_pk_bf16_f32 v0, v0, v1
	v_cvt_pk_bf16_f32 v1, v2, v3
	global_store_dwordx2 v[72:73], v[16:17], off offset:16
	v_pk_mul_f32 v[16:17], v[24:25], v[70:71] op_sel_hi:[1,0]
	v_pk_mul_f32 v[18:19], v[26:27], v[70:71] op_sel_hi:[1,0]
	global_store_dwordx2 v[72:73], v[0:1], off offset:80
	v_pk_mul_f32 v[0:1], v[8:9], v[70:71] op_sel_hi:[1,0]
	v_pk_mul_f32 v[2:3], v[10:11], v[70:71] op_sel_hi:[1,0]
	v_cvt_pk_bf16_f32 v16, v16, v17
	v_cvt_pk_bf16_f32 v17, v18, v19
	v_cvt_pk_bf16_f32 v0, v0, v1
	v_cvt_pk_bf16_f32 v1, v2, v3
	global_store_dwordx2 v[72:73], v[16:17], off offset:32
	v_pk_mul_f32 v[16:17], v[28:29], v[70:71] op_sel_hi:[1,0]
	v_pk_mul_f32 v[18:19], v[30:31], v[70:71] op_sel_hi:[1,0]
	global_store_dwordx2 v[72:73], v[0:1], off offset:96
	v_pk_mul_f32 v[0:1], v[12:13], v[70:71] op_sel_hi:[1,0]
	v_pk_mul_f32 v[2:3], v[14:15], v[70:71] op_sel_hi:[1,0]
	v_cvt_pk_bf16_f32 v16, v16, v17
	v_cvt_pk_bf16_f32 v17, v18, v19
	v_cvt_pk_bf16_f32 v0, v0, v1
	v_cvt_pk_bf16_f32 v1, v2, v3
	s_and_b64 vcc, exec, s[26:27]
	global_store_dwordx2 v[72:73], v[16:17], off offset:48
	global_store_dwordx2 v[72:73], v[0:1], off offset:112
	s_cbranch_vccz .LBB0_698
	ds_bpermute_b32 v2, v68, v64
	v_add_u32_e32 v0, 32, v66
	v_ashrrev_i32_e32 v1, 31, v0
	v_lshlrev_b64 v[0:1], 11, v[0:1]
	v_lshl_add_u64 v[0:1], v[174:175], 0, v[0:1]
	s_waitcnt lgkmcnt(0)
	v_add_f32_e32 v2, v64, v2
	v_div_scale_f32 v3, s[0:1], v2, v2, 1.0
	v_rcp_f32_e32 v4, v3
	v_div_scale_f32 v5, vcc, 1.0, v2, 1.0
	s_mov_b64 s[0:1], 0
	v_fma_f32 v6, -v3, v4, 1.0
	v_fmac_f32_e32 v4, v6, v4
	v_mul_f32_e32 v6, v5, v4
	v_fma_f32 v7, -v3, v6, v5
	v_fmac_f32_e32 v6, v7, v4
	v_fma_f32 v3, -v3, v6, v5
	v_div_fmas_f32 v3, v3, v4, v6
	v_div_fixup_f32 v2, v3, v2, 1.0
	v_pk_mul_f32 v[4:5], v[48:49], v[2:3] op_sel_hi:[1,0]
	v_pk_mul_f32 v[6:7], v[50:51], v[2:3] op_sel_hi:[1,0]
	v_cvt_pk_bf16_f32 v4, v4, v5
	v_cvt_pk_bf16_f32 v5, v6, v7
	global_store_dwordx2 v[0:1], v[4:5], off
	v_pk_mul_f32 v[4:5], v[52:53], v[2:3] op_sel_hi:[1,0]
	v_pk_mul_f32 v[6:7], v[54:55], v[2:3] op_sel_hi:[1,0]
	v_cvt_pk_bf16_f32 v4, v4, v5
	v_cvt_pk_bf16_f32 v5, v6, v7
	global_store_dwordx2 v[0:1], v[4:5], off offset:16
	v_pk_mul_f32 v[4:5], v[56:57], v[2:3] op_sel_hi:[1,0]
	v_pk_mul_f32 v[6:7], v[58:59], v[2:3] op_sel_hi:[1,0]
	v_cvt_pk_bf16_f32 v4, v4, v5
	v_cvt_pk_bf16_f32 v5, v6, v7
	global_store_dwordx2 v[0:1], v[4:5], off offset:32
	v_pk_mul_f32 v[4:5], v[60:61], v[2:3] op_sel_hi:[1,0]
	v_pk_mul_f32 v[6:7], v[62:63], v[2:3] op_sel_hi:[1,0]
	v_cvt_pk_bf16_f32 v4, v4, v5
	v_cvt_pk_bf16_f32 v5, v6, v7
	global_store_dwordx2 v[0:1], v[4:5], off offset:48
	v_pk_mul_f32 v[4:5], v[32:33], v[2:3] op_sel_hi:[1,0]
	v_pk_mul_f32 v[6:7], v[34:35], v[2:3] op_sel_hi:[1,0]
	v_cvt_pk_bf16_f32 v4, v4, v5
	v_cvt_pk_bf16_f32 v5, v6, v7
	global_store_dwordx2 v[0:1], v[4:5], off offset:64
	v_pk_mul_f32 v[4:5], v[36:37], v[2:3] op_sel_hi:[1,0]
	v_pk_mul_f32 v[6:7], v[38:39], v[2:3] op_sel_hi:[1,0]
	v_cvt_pk_bf16_f32 v4, v4, v5
	v_cvt_pk_bf16_f32 v5, v6, v7
	global_store_dwordx2 v[0:1], v[4:5], off offset:80
	v_pk_mul_f32 v[4:5], v[40:41], v[2:3] op_sel_hi:[1,0]
	v_pk_mul_f32 v[6:7], v[42:43], v[2:3] op_sel_hi:[1,0]
	v_cvt_pk_bf16_f32 v4, v4, v5
	v_cvt_pk_bf16_f32 v5, v6, v7
	global_store_dwordx2 v[0:1], v[4:5], off offset:96
	v_pk_mul_f32 v[4:5], v[44:45], v[2:3] op_sel_hi:[1,0]
	v_pk_mul_f32 v[2:3], v[46:47], v[2:3] op_sel_hi:[1,0]
	v_cvt_pk_bf16_f32 v4, v4, v5
	v_cvt_pk_bf16_f32 v5, v2, v3
	global_store_dwordx2 v[0:1], v[4:5], off offset:112
	s_branch .LBB0_699
